# retention P tiles also in MFMA-fragment order (ret_p stores, ret_scan loads)
# speedup vs baseline: 1.0462x; 1.0093x over previous
; __device__ __forceinline__ void ret_scan_unit(unsigned char* smem, const bf16_t* __restrict__ Q, const bf16_t* __restrict__ K, const bf16_t* __restrict__ V,
;                                               const bf16_t* __restrict__ Pt, bf16_t* OX, int b, int h, int dvs, const float* lg) {
;     ...
;         const float lgd = __uint_as_float(__builtin_amdgcn_readfirstlane(__float_as_uint(lg[dir * 4 + h])));
;         const float gC = __uint_as_float(__builtin_amdgcn_readfirstlane(__float_as_uint(__builtin_amdgcn_exp2f(128.f * lgd))));
;         f32x16 S[2];
; #pragma unroll
;         for (int d = 0; d < 2; ++d)
; #pragma unroll
;             for (int r = 0; r < 16; ++r) S[d][r] = 0.f;
;         u32x4 kv[8], vv[2];
;         for (int step = 0; step < 18; ++step) {
;             int ci;
;             if (step < 2) ci = dir ? 1 - step : step; else ci = dir ? 2 + (15 - (step - 2)) : step;
;             const int row0 = ci < 2 ? ML + b * CTXL + 128 * ci : b * SEQL + 128 * (ci - 2);
;             int tid = tid0; asm volatile("" : "+v"(tid));
;             const int lane = tid & 63, w = __builtin_amdgcn_readfirstlane(tid >> 6), h2 = lane >> 5, l31 = lane & 31, dvb = w & 1, ib = w >> 1;
;             const int trl = ((lane >> 4) & 1) * 32 + (lane & 3) * 8;
;             const int trr = ((lane & 15) >> 2);
;             bf16x8 qf[16], pfr[8];
;             {
;                 const bf16_t* qp = Q + (size_t)(row0 + 32 * ib + l31) * 1024 + h * 256 + 8 * h2;
; #pragma unroll
;                 for (int f = 0; f < 16; ++f) qf[f] = *(const bf16x8*)(qp + 16 * f);
;                 const bf16_t* pp = Pt + ((size_t)((dir * 8 + b) * 4 + h) * 18 + ci) * 16384 + (size_t)(32 * ib + l31) * 128 + 8 * h2;
.LBB0_391:
	s_lshl_b32 s2, s92, 2
	s_or_b32 s22, s2, s89
	s_lshl_b64 s[2:3], s[22:23], 2
	s_add_u32 s2, s78, s2
	s_addc_u32 s3, s79, s3
	global_load_dword v10, v181, s[2:3]
	v_add_co_u32_e64 v11, s[38:39], s92, -1
	s_lshl_b32 s2, s92, 5
	s_xor_b64 s[16:17], s[38:39], -1
	s_add_i32 s2, s2, s88
	s_waitcnt vmcnt(0)
	v_mov_b32_e32 v151, v183
	s_and_b64 vcc, s[38:39], exec
	s_mul_hi_i32 s93, s2, 18
	v_readfirstlane_b32 s3, v151
	s_mul_i32 s94, s2, 18
	s_cselect_b32 s2, 0x80, 0
	s_ashr_i32 s4, s3, 2
	s_or_b32 s6, s2, s91
	s_and_b32 s2, s4, 0xffffffe0
	v_and_b32_e32 v73, 31, v151
	s_add_i32 s7, s2, s6
	v_or_b32_e32 v0, s7, v73
	v_ashrrev_i32_e32 v1, 31, v0
	v_bfe_u32 v155, v151, 5, 1
	v_lshlrev_b64 v[0:1], 11, v[0:1]
	v_cndmask_b32_e64 v6, 0, 1, s[38:39]
	v_lshl_add_u64 v[0:1], s[46:47], 0, v[0:1]
	v_lshlrev_b32_e32 v180, 4, v155
	v_mov_b32_e32 v8, s4
	s_lshl_b32 s100, s89, 14
	s_add_u32 s100, s80, s100
	s_addc_u32 s101, s81, 0
	s_lshl_b32 s98, s7, 11
	s_add_u32 s100, s100, s98
	s_addc_u32 s101, s101, 0
	v_lshlrev_b32_e32 v238, 4, v73
	v_lshl_or_b32 v238, v155, 9, v238

; __device__ __forceinline__ void ret_scan_unit(unsigned char* smem, const bf16_t* __restrict__ Q, const bf16_t* __restrict__ K, const bf16_t* __restrict__ V,
;                                               const bf16_t* __restrict__ Pt, bf16_t* OX, int b, int h, int dvs, const float* lg) {
;     ...
;                 const bf16_t* qp = Q + (size_t)(row0 + 32 * ib + l31) * 1024 + h * 256 + 8 * h2;
; #pragma unroll
;                 for (int f = 0; f < 16; ++f) qf[f] = *(const bf16x8*)(qp + 16 * f);
;                 const bf16_t* pp = Pt + ((size_t)((dir * 8 + b) * 4 + h) * 18 + ci) * 16384 + (size_t)(32 * ib + l31) * 128 + 8 * h2;
	v_or_b32_e32 v6, s94, v6
	v_mov_b32_e32 v7, s93
	v_bfi_b32 v8, s1, v8, v151
	global_load_dwordx4 v[0:3], v238, s[100:101]
	global_load_dwordx4 v[144:147], v238, s[100:101] offset:1024
	global_load_dwordx4 v[136:139], v238, s[100:101] offset:2048
	global_load_dwordx4 v[128:131], v238, s[100:101] offset:3072
	s_add_u32 s100, s100, 0x1000
	s_addc_u32 s101, s101, 0

; __device__ __forceinline__ void ret_scan_unit(unsigned char* smem, const bf16_t* __restrict__ Q, const bf16_t* __restrict__ K, const bf16_t* __restrict__ V,
;                                               const bf16_t* __restrict__ Pt, bf16_t* OX, int b, int h, int dvs, const float* lg) {
;     ...
;                 const bf16_t* qp = Q + (size_t)(row0 + 32 * ib + l31) * 1024 + h * 256 + 8 * h2;
; #pragma unroll
;                 for (int f = 0; f < 16; ++f) qf[f] = *(const bf16x8*)(qp + 16 * f);
	global_load_dwordx4 v[124:127], v238, s[100:101]
	global_load_dwordx4 v[120:123], v238, s[100:101] offset:1024
	global_load_dwordx4 v[116:119], v238, s[100:101] offset:2048
	global_load_dwordx4 v[112:115], v238, s[100:101] offset:3072
	s_add_u32 s100, s100, 0x1000
	s_addc_u32 s101, s101, 0

; __device__ __forceinline__ void ret_scan_unit(unsigned char* smem, const bf16_t* __restrict__ Q, const bf16_t* __restrict__ K, const bf16_t* __restrict__ V,
;                                               const bf16_t* __restrict__ Pt, bf16_t* OX, int b, int h, int dvs, const float* lg) {
;     ...
;                 const bf16_t* qp = Q + (size_t)(row0 + 32 * ib + l31) * 1024 + h * 256 + 8 * h2;
; #pragma unroll
;                 for (int f = 0; f < 16; ++f) qf[f] = *(const bf16x8*)(qp + 16 * f);
	global_load_dwordx4 v[108:111], v238, s[100:101]
	global_load_dwordx4 v[104:107], v238, s[100:101] offset:1024
	global_load_dwordx4 v[100:103], v238, s[100:101] offset:2048
	global_load_dwordx4 v[96:99], v238, s[100:101] offset:3072
	s_add_u32 s100, s100, 0x1000
	s_addc_u32 s101, s101, 0

; __device__ __forceinline__ void ret_scan_unit(unsigned char* smem, const bf16_t* __restrict__ Q, const bf16_t* __restrict__ K, const bf16_t* __restrict__ V,
;                                               const bf16_t* __restrict__ Pt, bf16_t* OX, int b, int h, int dvs, const float* lg) {
;     ...
;                 const bf16_t* qp = Q + (size_t)(row0 + 32 * ib + l31) * 1024 + h * 256 + 8 * h2;
; #pragma unroll
;                 for (int f = 0; f < 16; ++f) qf[f] = *(const bf16x8*)(qp + 16 * f);
;                 const bf16_t* pp = Pt + ((size_t)((dir * 8 + b) * 4 + h) * 18 + ci) * 16384 + (size_t)(32 * ib + l31) * 128 + 8 * h2;
	global_load_dwordx4 v[92:95], v238, s[100:101]
	global_load_dwordx4 v[88:91], v238, s[100:101] offset:1024
	v_lshlrev_b64 v[6:7], 15, v[6:7]
	v_and_b32_e32 v9, 31, v8
	v_lshlrev_b32_e32 v9, 4, v9
	v_and_b32_e32 v8, 0xffffffe0, v8
	v_lshl_add_u32 v8, v8, 8, v9
	v_lshl_add_u32 v8, v155, 9, v8
	v_mov_b32_e32 v9, 0

; __device__ __forceinline__ void ret_scan_unit(unsigned char* smem, const bf16_t* __restrict__ Q, const bf16_t* __restrict__ K, const bf16_t* __restrict__ V,
;                                               const bf16_t* __restrict__ Pt, bf16_t* OX, int b, int h, int dvs, const float* lg) {
;     ...
;                 const bf16_t* pp = Pt + ((size_t)((dir * 8 + b) * 4 + h) * 18 + ci) * 16384 + (size_t)(32 * ib + l31) * 128 + 8 * h2;
	v_lshl_add_u64 v[6:7], s[44:45], 0, v[6:7]
	v_lshl_add_u64 v[6:7], v[6:7], 0, v[8:9]
	s_mov_b64 s[98:99], 0x1000
	v_lshl_add_u64 v[240:241], v[6:7], 0, s[98:99]

; __device__ __forceinline__ void ret_scan_unit(unsigned char* smem, const bf16_t* __restrict__ Q, const bf16_t* __restrict__ K, const bf16_t* __restrict__ V,
;                                               const bf16_t* __restrict__ Pt, bf16_t* OX, int b, int h, int dvs, const float* lg) {
;     ...
;                 for (int f = 0; f < 16; ++f) qf[f] = *(const bf16x8*)(qp + 16 * f);
;                 const bf16_t* pp = Pt + ((size_t)((dir * 8 + b) * 4 + h) * 18 + ci) * 16384 + (size_t)(32 * ib + l31) * 128 + 8 * h2;
; #pragma unroll
;                 for (int ks = 0; ks < 8; ++ks) pfr[ks] = *(const bf16x8*)(pp + ks * 16);
	global_load_dwordx4 v[44:47], v[6:7], off
	global_load_dwordx4 v[40:43], v[6:7], off offset:1024
	global_load_dwordx4 v[36:39], v[6:7], off offset:2048
	global_load_dwordx4 v[32:35], v[6:7], off offset:3072
	global_load_dwordx4 v[28:31], v[240:241], off
	global_load_dwordx4 v[24:27], v[240:241], off offset:1024
	global_load_dwordx4 v[20:23], v[240:241], off offset:2048
	global_load_dwordx4 v[16:19], v[240:241], off offset:3072
	global_load_dwordx4 v[140:143], v238, s[100:101] offset:2048
	global_load_dwordx4 v[132:135], v238, s[100:101] offset:3072

; __device__ __forceinline__ void ret_scan_unit(unsigned char* smem, const bf16_t* __restrict__ Q, const bf16_t* __restrict__ K, const bf16_t* __restrict__ V,
;                                               const bf16_t* __restrict__ Pt, bf16_t* OX, int b, int h, int dvs, const float* lg) {
;     ...
;         const float gC = __uint_as_float(__builtin_amdgcn_readfirstlane(__float_as_uint(__builtin_amdgcn_exp2f(128.f * lgd))));
;     ...
;             bf16_t* op = OX + (size_t)(row0 + 32 * ib + (l31 & 3) + 4 * h2) * 2048 + h * 512 + dvs * 64 + dvb * 32 + 4 * (l31 >> 2);
;             u32x2 prev2[4];
;             if (dir == 0) {
; #pragma unroll
;                 for (int j = 0; j < 4; ++j) prev2[j] = *(const u32x2*)(op + (size_t)(8 * j) * 2048);
	v_and_b32_e32 v4, 3, v151
	v_lshlrev_b32_e32 v154, 2, v155
	v_or3_b32 v4, v154, v4, s7
	v_ashrrev_i32_e32 v5, 31, v4
	s_bfe_u32 s8, s3, 0x10006
	v_lshlrev_b64 v[4:5], 12, v[4:5]
	v_and_b32_e32 v6, 28, v151
	s_lshl_b32 s22, s8, 6
	v_lshl_add_u64 v[4:5], s[52:53], 0, v[4:5]
	v_lshl_add_u64 v[4:5], v[4:5], 0, s[22:23]
	v_lshlrev_b32_e32 v180, 1, v6
	s_mov_b32 s4, 0
	v_readfirstlane_b32 s95, v11
	s_lshl_b32 s5, s8, 5
	v_lshl_add_u64 v[148:149], v[4:5], 0, v[180:181]
	s_waitcnt vmcnt(0)
	v_readfirstlane_b32 s96, v10
	s_nop 1
	v_mul_f32_e32 v7, s96, v199
	v_exp_f32_e32 v7, v7
	s_nop 0
	v_readfirstlane_b32 s58, v7
	s_cbranch_vccnz .LBB0_393
	v_add_co_u32_e32 v4, vcc, 0x8000, v148
	s_movk_i32 s4, 0x80
	s_nop 0
	v_addc_co_u32_e32 v5, vcc, 0, v149, vcc
	v_add_co_u32_e32 v6, vcc, 0x10000, v148
	s_nop 1
	v_addc_co_u32_e32 v7, vcc, 0, v149, vcc
	v_add_co_u32_e32 v8, vcc, 0x18000, v148
	s_nop 1
	v_addc_co_u32_e32 v9, vcc, 0, v149, vcc
	global_load_dwordx2 v[184:185], v[148:149], off
	global_load_dwordx2 v[186:187], v[4:5], off
	global_load_dwordx2 v[188:189], v[6:7], off
	global_load_dwordx2 v[190:191], v[8:9], off

; __device__ __forceinline__ void ret_scan_unit(unsigned char* smem, const bf16_t* __restrict__ Q, const bf16_t* __restrict__ K, const bf16_t* __restrict__ V,
;                                               const bf16_t* __restrict__ Pt, bf16_t* OX, int b, int h, int dvs, const float* lg) {
;     ...
;         for (int step = 0; step < 18; ++step) {
;             int ci;
;             if (step < 2) ci = dir ? 1 - step : step; else ci = dir ? 2 + (15 - (step - 2)) : step;
;             const int row0 = ci < 2 ? ML + b * CTXL + 128 * ci : b * SEQL + 128 * (ci - 2);
;             int tid = tid0; asm volatile("" : "+v"(tid));
;             const int lane = tid & 63, w = __builtin_amdgcn_readfirstlane(tid >> 6), h2 = lane >> 5, l31 = lane & 31, dvb = w & 1, ib = w >> 1;
;             const int trl = ((lane >> 4) & 1) * 32 + (lane & 3) * 8;
;             const int trr = ((lane & 15) >> 2);
;             bf16x8 qf[16], pfr[8];
;             {
;                 const bf16_t* qp = Q + (size_t)(row0 + 32 * ib + l31) * 1024 + h * 256 + 8 * h2;
; #pragma unroll
;                 for (int f = 0; f < 16; ++f) qf[f] = *(const bf16x8*)(qp + 16 * f);
;                 const bf16_t* pp = Pt + ((size_t)((dir * 8 + b) * 4 + h) * 18 + ci) * 16384 + (size_t)(32 * ib + l31) * 128 + 8 * h2;
.LBB0_403:
	s_add_i32 s5, s4, -1
	s_sub_i32 s6, s8, 17
	s_and_b64 s[2:3], s[38:39], exec
	s_cselect_b32 s6, s6, s5
	s_add_i32 s7, s8, 1
	s_and_b64 s[2:3], s[38:39], exec
	s_cselect_b32 s2, s7, s5
	s_cmp_lt_u32 s5, 2
	s_cselect_b32 s3, s6, s2
	s_lshl_b32 s2, s3, 7
	s_or_b32 s6, s2, s91
	s_add_i32 s2, s2, s90
	s_cmp_lt_u32 s3, 2
	v_mov_b32_e32 v209, v183
	s_cselect_b32 s6, s6, s2
	s_nop 0
	v_readfirstlane_b32 s2, v209
	s_ashr_i32 s9, s2, 2
	s_and_b32 s7, s9, 0xffffffe0
	v_and_b32_e32 v37, 31, v209
	s_add_i32 s6, s6, s7
	v_or_b32_e32 v32, s6, v37
	v_ashrrev_i32_e32 v33, 31, v32
	v_bfe_u32 v36, v209, 5, 1
	v_lshlrev_b64 v[32:33], 11, v[32:33]
	v_lshl_add_u64 v[32:33], s[46:47], 0, v[32:33]
	v_lshlrev_b32_e32 v180, 4, v36
	s_lshl_b32 s100, s89, 14
	s_add_u32 s100, s80, s100
	s_addc_u32 s101, s81, 0
	s_lshl_b32 s98, s6, 11
	s_add_u32 s100, s100, s98
	s_addc_u32 s101, s101, 0
	v_lshlrev_b32_e32 v38, 4, v37
	v_lshl_or_b32 v38, v36, 9, v38

; __device__ __forceinline__ void ret_scan_unit(unsigned char* smem, const bf16_t* __restrict__ Q, const bf16_t* __restrict__ K, const bf16_t* __restrict__ V,
;                                               const bf16_t* __restrict__ Pt, bf16_t* OX, int b, int h, int dvs, const float* lg) {
;     ...
;                 for (int f = 0; f < 16; ++f) qf[f] = *(const bf16x8*)(qp + 16 * f);
	global_load_dwordx4 v[32:35], v38, s[100:101]
	global_load_dwordx4 v[176:179], v38, s[100:101] offset:1024
	global_load_dwordx4 v[172:175], v38, s[100:101] offset:2048
	global_load_dwordx4 v[168:171], v38, s[100:101] offset:3072
	s_add_u32 s100, s100, 0x1000
	s_addc_u32 s101, s101, 0

; __device__ __forceinline__ void ret_scan_unit(unsigned char* smem, const bf16_t* __restrict__ Q, const bf16_t* __restrict__ K, const bf16_t* __restrict__ V,
;                                               const bf16_t* __restrict__ Pt, bf16_t* OX, int b, int h, int dvs, const float* lg) {
;     ...
;                 for (int f = 0; f < 16; ++f) qf[f] = *(const bf16x8*)(qp + 16 * f);
	global_load_dwordx4 v[164:167], v38, s[100:101]
	global_load_dwordx4 v[160:163], v38, s[100:101] offset:1024
	global_load_dwordx4 v[156:159], v38, s[100:101] offset:2048
	global_load_dwordx4 v[152:155], v38, s[100:101] offset:3072
	s_add_u32 s100, s100, 0x1000
	s_addc_u32 s101, s101, 0

; __device__ __forceinline__ void ret_scan_unit(unsigned char* smem, const bf16_t* __restrict__ Q, const bf16_t* __restrict__ K, const bf16_t* __restrict__ V,
;                                               const bf16_t* __restrict__ Pt, bf16_t* OX, int b, int h, int dvs, const float* lg) {
;     ...
;                 for (int f = 0; f < 16; ++f) qf[f] = *(const bf16x8*)(qp + 16 * f);
	global_load_dwordx4 v[148:151], v38, s[100:101]
	global_load_dwordx4 v[144:147], v38, s[100:101] offset:1024
	global_load_dwordx4 v[140:143], v38, s[100:101] offset:2048
	global_load_dwordx4 v[136:139], v38, s[100:101] offset:3072
	s_add_u32 s100, s100, 0x1000
	s_addc_u32 s101, s101, 0

; __device__ __forceinline__ void ret_scan_unit(unsigned char* smem, const bf16_t* __restrict__ Q, const bf16_t* __restrict__ K, const bf16_t* __restrict__ V,
;                                               const bf16_t* __restrict__ Pt, bf16_t* OX, int b, int h, int dvs, const float* lg) {
;     ...
;                 for (int f = 0; f < 16; ++f) qf[f] = *(const bf16x8*)(qp + 16 * f);
;                 const bf16_t* pp = Pt + ((size_t)((dir * 8 + b) * 4 + h) * 18 + ci) * 16384 + (size_t)(32 * ib + l31) * 128 + 8 * h2;
; #pragma unroll
;                 for (int ks = 0; ks < 8; ++ks) pfr[ks] = *(const bf16x8*)(pp + ks * 16);
	global_load_dwordx4 v[132:135], v38, s[100:101]
	global_load_dwordx4 v[128:131], v38, s[100:101] offset:1024
	global_load_dwordx4 v[124:127], v38, s[100:101] offset:2048
	global_load_dwordx4 v[120:123], v38, s[100:101] offset:3072
	s_add_u32 s42, s94, s3
	s_addc_u32 s43, s93, 0
	s_lshl_b64 s[42:43], s[42:43], 15
	s_add_u32 s42, s44, s42
	s_addc_u32 s43, s45, s43
	v_mov_b32_e32 v38, s9
	v_bfi_b32 v38, s1, v38, v209
	v_and_b32_e32 v39, 31, v38
	v_lshlrev_b32_e32 v39, 4, v39
	v_and_b32_e32 v38, 0xffffffe0, v38
	v_lshl_add_u32 v38, v38, 8, v39
	v_lshl_add_u32 v38, v36, 9, v38
	s_mov_b64 s[100:101], s[42:43]

; __device__ __forceinline__ void ret_scan_unit(unsigned char* smem, const bf16_t* __restrict__ Q, const bf16_t* __restrict__ K, const bf16_t* __restrict__ V,
;                                               const bf16_t* __restrict__ Pt, bf16_t* OX, int b, int h, int dvs, const float* lg) {
;     ...
;                 const bf16_t* pp = Pt + ((size_t)((dir * 8 + b) * 4 + h) * 18 + ci) * 16384 + (size_t)(32 * ib + l31) * 128 + 8 * h2;
; #pragma unroll
;                 for (int ks = 0; ks < 8; ++ks) pfr[ks] = *(const bf16x8*)(pp + ks * 16);
	global_load_dwordx4 v[116:119], v38, s[100:101]
	global_load_dwordx4 v[112:115], v38, s[100:101] offset:1024
	global_load_dwordx4 v[108:111], v38, s[100:101] offset:2048
	global_load_dwordx4 v[104:107], v38, s[100:101] offset:3072
	s_add_u32 s100, s100, 0x1000
	s_addc_u32 s101, s101, 0

; __device__ __forceinline__ void ret_scan_unit(unsigned char* smem, const bf16_t* __restrict__ Q, const bf16_t* __restrict__ K, const bf16_t* __restrict__ V,
;                                               const bf16_t* __restrict__ Pt, bf16_t* OX, int b, int h, int dvs, const float* lg) {
;     ...
;                 const bf16_t* pp = Pt + ((size_t)((dir * 8 + b) * 4 + h) * 18 + ci) * 16384 + (size_t)(32 * ib + l31) * 128 + 8 * h2;
; #pragma unroll
;                 for (int ks = 0; ks < 8; ++ks) pfr[ks] = *(const bf16x8*)(pp + ks * 16);
;             }
;             bf16_t* op = OX + (size_t)(row0 + 32 * ib + (l31 & 3) + 4 * h2) * 2048 + h * 512 + dvs * 64 + dvb * 32 + 4 * (l31 >> 2);
;             u32x2 prev2[4];
;             if (dir == 0) {
; #pragma unroll
;                 for (int j = 0; j < 4; ++j) prev2[j] = *(const u32x2*)(op + (size_t)(8 * j) * 2048);
	global_load_dwordx4 v[100:103], v38, s[100:101]
	global_load_dwordx4 v[96:99], v38, s[100:101] offset:1024
	global_load_dwordx4 v[92:95], v38, s[100:101] offset:2048
	global_load_dwordx4 v[88:91], v38, s[100:101] offset:3072
	v_and_b32_e32 v38, 3, v209
	v_lshlrev_b32_e32 v211, 2, v36
	v_or3_b32 v38, v211, v38, s6
	v_ashrrev_i32_e32 v39, 31, v38
	s_bfe_u32 s3, s2, 0x10006
	v_lshlrev_b64 v[38:39], 12, v[38:39]
	v_lshl_add_u64 v[38:39], s[52:53], 0, v[38:39]
	s_lshl_b32 s22, s3, 6
	v_and_b32_e32 v40, 28, v209
	v_lshl_add_u64 v[38:39], v[38:39], 0, s[22:23]
	v_lshlrev_b32_e32 v180, 1, v40
	s_and_b64 vcc, exec, s[40:41]
	v_lshl_add_u64 v[192:193], v[38:39], 0, v[180:181]
	s_cbranch_vccnz .LBB0_405
	v_add_co_u32_e32 v38, vcc, 0x8000, v192
	s_nop 1
	v_addc_co_u32_e32 v39, vcc, 0, v193, vcc
	v_add_co_u32_e32 v40, vcc, 0x10000, v192
	s_nop 1
	v_addc_co_u32_e32 v41, vcc, 0, v193, vcc
	v_add_co_u32_e32 v42, vcc, 0x18000, v192
	s_nop 1
	v_addc_co_u32_e32 v43, vcc, 0, v193, vcc
	global_load_dwordx2 v[184:185], v[192:193], off
	global_load_dwordx2 v[186:187], v[38:39], off
	global_load_dwordx2 v[188:189], v[40:41], off
	global_load_dwordx2 v[190:191], v[42:43], off

; __device__ __forceinline__ void ret_p_unit(const bf16_t* __restrict__ Q, const bf16_t* __restrict__ K, bf16_t* Pt, int b, int h, int ci, float lgf, float lgb) {
;     ...
;     const int row0 = ci < 2 ? ML + b * CTXL + 128 * ci : b * SEQL + 128 * (ci - 2);
;     const int ib = w & 3, jh = w >> 2;
;     const bf16_t* qp = Q + (size_t)(row0 + 32 * ib + l31) * 1024 + h * 256 + h2 * 8;
;     f32x16 s[2];
; #pragma unroll
;     for (int jb = 0; jb < 2; ++jb)
; #pragma unroll
;         for (int r = 0; r < 16; ++r) s[jb][r] = 0.f;
;     const bf16_t* kp0 = K + (size_t)(row0 + 64 * jh + l31) * 1024 + h * 256 + h2 * 8;
.LBB0_597:
	v_lshrrev_b32_e32 v2, 1, v36
	v_and_b32_e32 v38, 31, v36
	v_and_b32_e32 v37, 0x60, v2
	s_lshl_b32 s2, s16, 8
	v_ashrrev_i32_e32 v0, 2, v36
	s_ashr_i32 s3, s2, 31
	v_and_b32_e32 v39, 0xffffffc0, v0
	v_add3_u32 v0, s6, v37, v38
	v_ashrrev_i32_e32 v1, 31, v0
	s_lshl_b64 s[2:3], s[2:3], 1
	v_lshlrev_b64 v[0:1], 11, v[0:1]
	v_and_b32_e32 v2, 16, v2
	s_add_u32 s8, s47, s2
	v_or_b32_e32 v0, v0, v2
	s_addc_u32 s9, s48, s3
	v_lshl_add_u64 v[32:33], s[8:9], 0, v[0:1]
	v_add3_u32 v0, s6, v39, v38
	v_ashrrev_i32_e32 v1, 31, v0
	v_lshlrev_b64 v[0:1], 11, v[0:1]
	s_add_u32 s2, s38, s2
	v_or_b32_e32 v0, v0, v2
	s_addc_u32 s3, s39, s3
	v_mov_b32_e32 v16, 0
	v_lshl_add_u64 v[34:35], s[2:3], 0, v[0:1]
	s_mov_b64 s[40:41], 0
	v_mov_b32_e32 v17, v16
	v_mov_b32_e32 v18, v16
	v_mov_b32_e32 v19, v16
	v_mov_b32_e32 v20, v16
	v_mov_b32_e32 v21, v16
	v_mov_b32_e32 v22, v16
	v_mov_b32_e32 v23, v16
	v_mov_b32_e32 v24, v16
	v_mov_b32_e32 v25, v16
	v_mov_b32_e32 v26, v16
	v_mov_b32_e32 v27, v16
	v_mov_b32_e32 v28, v16
	v_mov_b32_e32 v29, v16
	v_mov_b32_e32 v30, v16
	v_mov_b32_e32 v31, v16
	v_mov_b32_e32 v0, v16
	v_mov_b32_e32 v1, v16
	v_mov_b32_e32 v2, v16
	v_mov_b32_e32 v3, v16
	v_mov_b32_e32 v4, v16
	v_mov_b32_e32 v5, v16
	v_mov_b32_e32 v6, v16
	v_mov_b32_e32 v7, v16
	v_mov_b32_e32 v8, v16
	v_mov_b32_e32 v9, v16
	v_mov_b32_e32 v10, v16
	v_mov_b32_e32 v11, v16
	v_mov_b32_e32 v12, v16
	v_mov_b32_e32 v13, v16
	v_mov_b32_e32 v14, v16
	v_mov_b32_e32 v15, v16
	s_mov_b32 s2, 0x7400000
	v_add_co_u32_e32 v54, vcc, s2, v34
	s_mov_b32 s2, 0x7410000
	s_nop 0
	v_addc_co_u32_e32 v55, vcc, 0, v35, vcc
	v_add_co_u32_e32 v56, vcc, s2, v34
	s_nop 1
	v_addc_co_u32_e32 v57, vcc, 0, v35, vcc

; __device__ __forceinline__ void ret_p_unit(const bf16_t* __restrict__ Q, const bf16_t* __restrict__ K, bf16_t* Pt, int b, int h, int ci, float lgf, float lgb) {
;     ...
;     const bf16_t* qp = Q + (size_t)(row0 + 32 * ib + l31) * 1024 + h * 256 + h2 * 8;
;     f32x16 s[2];
; #pragma unroll
;     for (int jb = 0; jb < 2; ++jb)
; #pragma unroll
;         for (int r = 0; r < 16; ++r) s[jb][r] = 0.f;
;     const bf16_t* kp0 = K + (size_t)(row0 + 64 * jh + l31) * 1024 + h * 256 + h2 * 8;
; #pragma unroll 4
;     for (int ks = 0; ks < 16; ++ks) {
;         const bf16x8 a = *(const bf16x8*)(qp + ks * 16);
;         const bf16x8 b0 = *(const bf16x8*)(kp0 + ks * 16), b1 = *(const bf16x8*)(kp0 + 32 * 1024 + ks * 16);
	v_add_u32_e32 v58, s6, v37
	v_mov_b32_e32 v59, 0
	v_lshlrev_b64 v[58:59], 11, v[58:59]
	v_lshl_or_b32 v58, v38, 4, v58
	v_bfe_u32 v60, v36, 5, 1
	v_lshl_or_b32 v58, v60, 9, v58
	s_lshl_b32 s98, s16, 14
	s_add_u32 s98, s47, s98
	s_addc_u32 s99, s48, 0
	s_sub_u32 s98, s98, 64
	s_subb_u32 s99, s99, 0
	v_lshl_add_u64 v[58:59], s[98:99], 0, v[58:59]
	s_mov_b64 s[98:99], 0x1000
	v_lshl_add_u64 v[60:61], v[58:59], 0, s[98:99]
	v_lshl_add_u64 v[62:63], v[60:61], 0, s[98:99]
	v_lshl_add_u64 v[64:65], v[62:63], 0, s[98:99]

; __device__ __forceinline__ void ret_p_unit(const bf16_t* __restrict__ Q, const bf16_t* __restrict__ K, bf16_t* Pt, int b, int h, int ci, float lgf, float lgb) {
;     ...
; #pragma unroll 4
;     for (int ks = 0; ks < 16; ++ks) {
;         const bf16x8 a = *(const bf16x8*)(qp + ks * 16);
;         const bf16x8 b0 = *(const bf16x8*)(kp0 + ks * 16), b1 = *(const bf16x8*)(kp0 + 32 * 1024 + ks * 16);
;         s[0] = __builtin_amdgcn_mfma_f32_32x32x16_bf16(a, b0, s[0], 0, 0, 0);
;         s[1] = __builtin_amdgcn_mfma_f32_32x32x16_bf16(a, b1, s[1], 0, 0, 0);
;     }
	global_load_dwordx4 v[104:107], v[58:59], off
	global_load_dwordx4 v[108:111], v[54:55], off
	global_load_dwordx4 v[112:115], v[56:57], off
	global_load_dwordx4 v[116:119], v[58:59], off offset:1024
	global_load_dwordx4 v[120:123], v[54:55], off offset:32
	global_load_dwordx4 v[124:127], v[56:57], off offset:32
	global_load_dwordx4 v[128:131], v[58:59], off offset:2048
	global_load_dwordx4 v[132:135], v[54:55], off offset:64
	global_load_dwordx4 v[136:139], v[56:57], off offset:64
	global_load_dwordx4 v[140:143], v[58:59], off offset:3072
	global_load_dwordx4 v[144:147], v[54:55], off offset:96
	global_load_dwordx4 v[148:151], v[56:57], off offset:96
	global_load_dwordx4 v[152:155], v[60:61], off
	global_load_dwordx4 v[156:159], v[54:55], off offset:128
	global_load_dwordx4 v[160:163], v[56:57], off offset:128
	global_load_dwordx4 v[164:167], v[60:61], off offset:1024
	global_load_dwordx4 v[168:171], v[54:55], off offset:160
	global_load_dwordx4 v[172:175], v[56:57], off offset:160
	global_load_dwordx4 v[176:179], v[60:61], off offset:2048
	global_load_dwordx4 v[184:187], v[54:55], off offset:192
	global_load_dwordx4 v[188:191], v[56:57], off offset:192
	global_load_dwordx4 v[212:215], v[60:61], off offset:3072
	global_load_dwordx4 v[216:219], v[54:55], off offset:224
	global_load_dwordx4 v[220:223], v[56:57], off offset:224
	s_waitcnt vmcnt(22)
	v_mfma_f32_32x32x16_bf16 v[16:31], v[104:107], v[108:111], v[16:31]
	s_waitcnt vmcnt(21)
	v_mfma_f32_32x32x16_bf16 v[0:15], v[104:107], v[112:115], v[0:15]
	s_waitcnt vmcnt(19)
	v_mfma_f32_32x32x16_bf16 v[16:31], v[116:119], v[120:123], v[16:31]
	s_waitcnt vmcnt(18)
	v_mfma_f32_32x32x16_bf16 v[0:15], v[116:119], v[124:127], v[0:15]
	s_waitcnt vmcnt(16)
	v_mfma_f32_32x32x16_bf16 v[16:31], v[128:131], v[132:135], v[16:31]
	s_waitcnt vmcnt(15)
	v_mfma_f32_32x32x16_bf16 v[0:15], v[128:131], v[136:139], v[0:15]
	s_waitcnt vmcnt(13)
	v_mfma_f32_32x32x16_bf16 v[16:31], v[140:143], v[144:147], v[16:31]
	s_waitcnt vmcnt(12)
	v_mfma_f32_32x32x16_bf16 v[0:15], v[140:143], v[148:151], v[0:15]
	global_load_dwordx4 v[104:107], v[62:63], off
	global_load_dwordx4 v[108:111], v[54:55], off offset:256
	global_load_dwordx4 v[112:115], v[56:57], off offset:256
	global_load_dwordx4 v[116:119], v[62:63], off offset:1024
	global_load_dwordx4 v[120:123], v[54:55], off offset:288
	global_load_dwordx4 v[124:127], v[56:57], off offset:288
	global_load_dwordx4 v[128:131], v[62:63], off offset:2048
	global_load_dwordx4 v[132:135], v[54:55], off offset:320
	global_load_dwordx4 v[136:139], v[56:57], off offset:320
	global_load_dwordx4 v[140:143], v[62:63], off offset:3072
	global_load_dwordx4 v[144:147], v[54:55], off offset:352
	global_load_dwordx4 v[148:151], v[56:57], off offset:352
	s_waitcnt vmcnt(22)
	v_mfma_f32_32x32x16_bf16 v[16:31], v[152:155], v[156:159], v[16:31]
	s_waitcnt vmcnt(21)
	v_mfma_f32_32x32x16_bf16 v[0:15], v[152:155], v[160:163], v[0:15]
	s_waitcnt vmcnt(19)
	v_mfma_f32_32x32x16_bf16 v[16:31], v[164:167], v[168:171], v[16:31]
	s_waitcnt vmcnt(18)
	v_mfma_f32_32x32x16_bf16 v[0:15], v[164:167], v[172:175], v[0:15]
	s_waitcnt vmcnt(16)
	v_mfma_f32_32x32x16_bf16 v[16:31], v[176:179], v[184:187], v[16:31]
	s_waitcnt vmcnt(15)
	v_mfma_f32_32x32x16_bf16 v[0:15], v[176:179], v[188:191], v[0:15]
	s_waitcnt vmcnt(13)
	v_mfma_f32_32x32x16_bf16 v[16:31], v[212:215], v[216:219], v[16:31]
	s_waitcnt vmcnt(12)
	v_mfma_f32_32x32x16_bf16 v[0:15], v[212:215], v[220:223], v[0:15]
	global_load_dwordx4 v[152:155], v[64:65], off
	global_load_dwordx4 v[156:159], v[54:55], off offset:384
	global_load_dwordx4 v[160:163], v[56:57], off offset:384
	global_load_dwordx4 v[164:167], v[64:65], off offset:1024
	global_load_dwordx4 v[168:171], v[54:55], off offset:416
	global_load_dwordx4 v[172:175], v[56:57], off offset:416
	global_load_dwordx4 v[176:179], v[64:65], off offset:2048
	global_load_dwordx4 v[184:187], v[54:55], off offset:448
	global_load_dwordx4 v[188:191], v[56:57], off offset:448
	global_load_dwordx4 v[212:215], v[64:65], off offset:3072
	global_load_dwordx4 v[216:219], v[54:55], off offset:480
	global_load_dwordx4 v[220:223], v[56:57], off offset:480
	s_waitcnt vmcnt(22)
	v_mfma_f32_32x32x16_bf16 v[16:31], v[104:107], v[108:111], v[16:31]
	s_waitcnt vmcnt(21)
	v_mfma_f32_32x32x16_bf16 v[0:15], v[104:107], v[112:115], v[0:15]
	s_waitcnt vmcnt(19)
	v_mfma_f32_32x32x16_bf16 v[16:31], v[116:119], v[120:123], v[16:31]
	s_waitcnt vmcnt(18)
	v_mfma_f32_32x32x16_bf16 v[0:15], v[116:119], v[124:127], v[0:15]
	s_waitcnt vmcnt(16)
	v_mfma_f32_32x32x16_bf16 v[16:31], v[128:131], v[132:135], v[16:31]
	s_waitcnt vmcnt(15)
	v_mfma_f32_32x32x16_bf16 v[0:15], v[128:131], v[136:139], v[0:15]
	s_waitcnt vmcnt(13)
	v_mfma_f32_32x32x16_bf16 v[16:31], v[140:143], v[144:147], v[16:31]
	s_waitcnt vmcnt(12)
	v_mfma_f32_32x32x16_bf16 v[0:15], v[140:143], v[148:151], v[0:15]
	s_waitcnt vmcnt(10)
	v_mfma_f32_32x32x16_bf16 v[16:31], v[152:155], v[156:159], v[16:31]
	s_waitcnt vmcnt(9)
	v_mfma_f32_32x32x16_bf16 v[0:15], v[152:155], v[160:163], v[0:15]
	s_waitcnt vmcnt(7)
	v_mfma_f32_32x32x16_bf16 v[16:31], v[164:167], v[168:171], v[16:31]
	s_waitcnt vmcnt(6)
	v_mfma_f32_32x32x16_bf16 v[0:15], v[164:167], v[172:175], v[0:15]
	s_waitcnt vmcnt(4)
	v_mfma_f32_32x32x16_bf16 v[16:31], v[176:179], v[184:187], v[16:31]
	s_waitcnt vmcnt(3)
	v_mfma_f32_32x32x16_bf16 v[0:15], v[176:179], v[188:191], v[0:15]
	s_waitcnt vmcnt(1)
	v_mfma_f32_32x32x16_bf16 v[16:31], v[212:215], v[216:219], v[16:31]
	s_waitcnt vmcnt(0)
	v_mfma_f32_32x32x16_bf16 v[0:15], v[212:215], v[220:223], v[0:15]
	s_movk_i32 s40, 0x200
	s_mov_b32 s41, 0

; __device__ __forceinline__ int crow(int r, int h) { return (r & 3) + 8 * (r >> 2) + 4 * h; }
; __device__ __forceinline__ void ret_p_unit(const bf16_t* __restrict__ Q, const bf16_t* __restrict__ K, bf16_t* Pt, int b, int h, int ci, float lgf, float lgb) {
;     ...
;     bf16_t* pf = Pt + ((size_t)((0 * 8 + b) * 4 + h) * 18 + ci) * 16384;
;     bf16_t* pb = Pt + ((size_t)((1 * 8 + b) * 4 + h) * 18 + ci) * 16384;
; #pragma unroll
;     for (int jb = 0; jb < 2; ++jb)
; #pragma unroll
;         for (int r = 0; r < 16; ++r) {
;             const int i = 32 * ib + crow(r, h2), j = 64 * jh + 32 * jb + l31, df = i - j;
	v_lshrrev_b32_e32 v32, 3, v36
	v_or_b32_e32 v82, v39, v38
	v_lshrrev_b32_e32 v101, 4, v82
	v_lshlrev_b32_e32 v101, 9, v101
	v_bfe_u32 v102, v82, 3, 1
	v_lshl_or_b32 v101, v102, 8, v101
	v_and_b32_e32 v102, 7, v82
	v_or_b32_e32 v101, v101, v102
	v_lshl_add_u32 v101, v37, 7, v101

; __device__ __forceinline__ unsigned cvt_pk_bf16(float lo, float hi) { unsigned r; asm volatile("v_cvt_pk_bf16_f32 %0, %1, %2" : "=v"(r) : "v"(lo), "v"(hi)); return r; }
; __device__ __forceinline__ int crow(int r, int h) { return (r & 3) + 8 * (r >> 2) + 4 * h; }
; __device__ __forceinline__ void ret_p_unit(const bf16_t* __restrict__ Q, const bf16_t* __restrict__ K, bf16_t* Pt, int b, int h, int ci, float lgf, float lgb) {
;     ...
;     bf16_t* pf = Pt + ((size_t)((0 * 8 + b) * 4 + h) * 18 + ci) * 16384;
;     bf16_t* pb = Pt + ((size_t)((1 * 8 + b) * 4 + h) * 18 + ci) * 16384;
; #pragma unroll
;     for (int jb = 0; jb < 2; ++jb)
; #pragma unroll
;         for (int r = 0; r < 16; ++r) {
;             const int i = 32 * ib + crow(r, h2), j = 64 * jh + 32 * jb + l31, df = i - j;
;             const float v = s[jb][r];
;             const float vf = df >= 0 ? v * __builtin_amdgcn_exp2f((float)df * lgf) : 0.f;
;             const float vb = df < 0 ? v * __builtin_amdgcn_exp2f((float)(-df) * lgb) : 0.f;
;             pf[i * 128 + j] = (bf16_t)(cvt_pk_bf16(vf, vf) & 0xffffu);
;             pb[i * 128 + j] = (bf16_t)(cvt_pk_bf16(vb, vb) & 0xffffu);
	v_and_or_b32 v83, v32, 4, v37
	v_sub_u32_e32 v32, v83, v82
	v_cvt_f32_u32_e32 v33, v32
	v_cmp_lt_i32_e32 vcc, -1, v32
	s_lshl_b32 s2, s5, 2
	s_add_i32 s5, s16, s2
	v_mul_f32_e32 v33, v81, v33
	v_exp_f32_e32 v33, v33
	s_mul_i32 s6, s5, 18
	s_ashr_i32 s7, s4, 31
	s_mul_hi_i32 s3, s5, 18
	v_mul_f32_e32 v33, v33, v16
	v_cndmask_b32_e32 v33, 0, v33, vcc
	v_cmp_gt_i32_e32 vcc, 0, v32
	v_sub_u32_e32 v32, 0, v32
	v_cvt_f32_u32_e32 v32, v32
	s_add_u32 s2, s6, s4
	s_addc_u32 s3, s3, s7
	s_lshl_b64 s[2:3], s[2:3], 15
	v_mul_f32_e32 v32, v80, v32
	v_exp_f32_e32 v32, v32
	s_add_u32 s16, s45, s2
	s_addc_u32 s17, s46, s3
	s_add_i32 s5, s5, 32
	s_addk_i32 s6, 0x240
	s_mul_hi_i32 s3, s5, 18
	s_add_u32 s2, s6, s4
	s_addc_u32 s3, s3, s7
	v_mul_f32_e32 v16, v32, v16
	v_and_b32_e32 v32, 31, v83
	v_lshl_add_u32 v32, v32, 3, v101

; __device__ __forceinline__ unsigned cvt_pk_bf16(float lo, float hi) { unsigned r; asm volatile("v_cvt_pk_bf16_f32 %0, %1, %2" : "=v"(r) : "v"(lo), "v"(hi)); return r; }
; __device__ __forceinline__ int crow(int r, int h) { return (r & 3) + 8 * (r >> 2) + 4 * h; }
; __device__ __forceinline__ void ret_p_unit(const bf16_t* __restrict__ Q, const bf16_t* __restrict__ K, bf16_t* Pt, int b, int h, int ci, float lgf, float lgb) {
;     ...
;         for (int r = 0; r < 16; ++r) {
;             const int i = 32 * ib + crow(r, h2), j = 64 * jh + 32 * jb + l31, df = i - j;
;             const float v = s[jb][r];
;             const float vf = df >= 0 ? v * __builtin_amdgcn_exp2f((float)df * lgf) : 0.f;
;             const float vb = df < 0 ? v * __builtin_amdgcn_exp2f((float)(-df) * lgb) : 0.f;
;             pf[i * 128 + j] = (bf16_t)(cvt_pk_bf16(vf, vf) & 0xffffu);
;             pb[i * 128 + j] = (bf16_t)(cvt_pk_bf16(vb, vb) & 0xffffu);
	s_lshl_b64 s[2:3], s[2:3], 15
	v_cvt_pk_bf16_f32 v36, v33, v33
	v_ashrrev_i32_e32 v33, 31, v32
	s_add_u32 s40, s45, s2
	v_lshlrev_b64 v[34:35], 1, v[32:33]
	s_addc_u32 s41, s46, s3
	v_cndmask_b32_e32 v16, 0, v16, vcc
	v_lshl_add_u64 v[32:33], s[16:17], 0, v[34:35]
	global_store_short v[32:33], v36, off
	v_cvt_pk_bf16_f32 v16, v16, v16
	v_lshl_add_u64 v[34:35], s[40:41], 0, v[34:35]
	v_or_b32_e32 v84, 1, v83
	global_store_short v[34:35], v16, off
	v_sub_u32_e32 v16, v84, v82
	v_cvt_f32_u32_e32 v36, v16
	v_cmp_lt_i32_e32 vcc, -1, v16
	v_or_b32_e32 v85, 2, v83
	v_or_b32_e32 v86, 3, v83
	v_mul_f32_e32 v36, v81, v36
	v_exp_f32_e32 v36, v36
	v_or_b32_e32 v87, 8, v83
	v_or_b32_e32 v88, 9, v83
	v_or_b32_e32 v89, 10, v83
	v_mul_f32_e32 v36, v36, v17
	v_cndmask_b32_e32 v36, 0, v36, vcc
	v_cmp_gt_i32_e32 vcc, 0, v16
	v_sub_u32_e32 v16, 0, v16
	v_cvt_f32_u32_e32 v16, v16
	v_cvt_pk_bf16_f32 v39, v36, v36
	v_or_b32_e32 v90, 11, v83
	v_or_b32_e32 v91, 16, v83
	v_mul_f32_e32 v16, v80, v16
	v_exp_f32_e32 v16, v16
	v_or_b32_e32 v92, 17, v83
	v_or_b32_e32 v93, 18, v83
	v_or_b32_e32 v94, 19, v83
	v_mul_f32_e32 v16, v16, v17
	v_cndmask_b32_e32 v38, 0, v16, vcc
	v_and_b32_e32 v16, 31, v84
	v_lshl_add_u32 v16, v16, 3, v101

; __device__ __forceinline__ unsigned cvt_pk_bf16(float lo, float hi) { unsigned r; asm volatile("v_cvt_pk_bf16_f32 %0, %1, %2" : "=v"(r) : "v"(lo), "v"(hi)); return r; }
; __device__ __forceinline__ int crow(int r, int h) { return (r & 3) + 8 * (r >> 2) + 4 * h; }
; __device__ __forceinline__ void ret_p_unit(const bf16_t* __restrict__ Q, const bf16_t* __restrict__ K, bf16_t* Pt, int b, int h, int ci, float lgf, float lgb) {
;     ...
;         for (int r = 0; r < 16; ++r) {
;             const int i = 32 * ib + crow(r, h2), j = 64 * jh + 32 * jb + l31, df = i - j;
;             const float v = s[jb][r];
;             const float vf = df >= 0 ? v * __builtin_amdgcn_exp2f((float)df * lgf) : 0.f;
;             const float vb = df < 0 ? v * __builtin_amdgcn_exp2f((float)(-df) * lgb) : 0.f;
;             pf[i * 128 + j] = (bf16_t)(cvt_pk_bf16(vf, vf) & 0xffffu);
;             pb[i * 128 + j] = (bf16_t)(cvt_pk_bf16(vb, vb) & 0xffffu);
	v_ashrrev_i32_e32 v17, 31, v16
	v_lshlrev_b64 v[36:37], 1, v[16:17]
	v_lshl_add_u64 v[16:17], s[16:17], 0, v[36:37]
	global_store_short v[16:17], v39, off
	v_cvt_pk_bf16_f32 v38, v38, v38
	v_lshl_add_u64 v[36:37], s[40:41], 0, v[36:37]
	global_store_short v[36:37], v38, off
	v_sub_u32_e32 v38, v85, v82
	v_cvt_f32_u32_e32 v39, v38
	v_cmp_lt_i32_e32 vcc, -1, v38
	v_or_b32_e32 v95, 24, v83
	v_or_b32_e32 v96, 25, v83
	v_mul_f32_e32 v39, v81, v39
	v_exp_f32_e32 v39, v39
	v_or_b32_e32 v97, 26, v83
	v_or_b32_e32 v98, 27, v83
	s_add_i32 s42, s42, s22
	v_mul_f32_e32 v39, v39, v18
	v_cndmask_b32_e32 v39, 0, v39, vcc
	v_cmp_gt_i32_e32 vcc, 0, v38
	v_sub_u32_e32 v38, 0, v38
	v_cvt_f32_u32_e32 v38, v38
	v_cvt_pk_bf16_f32 v42, v39, v39
	s_cmpk_lt_i32 s42, 0x240
	v_mul_f32_e32 v38, v80, v38
	v_exp_f32_e32 v38, v38
	s_nop 0
	v_mul_f32_e32 v18, v38, v18
	v_and_b32_e32 v38, 31, v85
	v_lshl_add_u32 v38, v38, 3, v101

; __device__ __forceinline__ unsigned cvt_pk_bf16(float lo, float hi) { unsigned r; asm volatile("v_cvt_pk_bf16_f32 %0, %1, %2" : "=v"(r) : "v"(lo), "v"(hi)); return r; }
; __device__ __forceinline__ int crow(int r, int h) { return (r & 3) + 8 * (r >> 2) + 4 * h; }
; __device__ __forceinline__ void ret_p_unit(const bf16_t* __restrict__ Q, const bf16_t* __restrict__ K, bf16_t* Pt, int b, int h, int ci, float lgf, float lgb) {
;     ...
;         for (int r = 0; r < 16; ++r) {
;             const int i = 32 * ib + crow(r, h2), j = 64 * jh + 32 * jb + l31, df = i - j;
;             const float v = s[jb][r];
;             const float vf = df >= 0 ? v * __builtin_amdgcn_exp2f((float)df * lgf) : 0.f;
;             const float vb = df < 0 ? v * __builtin_amdgcn_exp2f((float)(-df) * lgb) : 0.f;
;             pf[i * 128 + j] = (bf16_t)(cvt_pk_bf16(vf, vf) & 0xffffu);
;             pb[i * 128 + j] = (bf16_t)(cvt_pk_bf16(vb, vb) & 0xffffu);
	v_ashrrev_i32_e32 v39, 31, v38
	v_lshlrev_b64 v[40:41], 1, v[38:39]
	v_cndmask_b32_e32 v18, 0, v18, vcc
	v_lshl_add_u64 v[38:39], s[16:17], 0, v[40:41]
	global_store_short v[38:39], v42, off
	v_cvt_pk_bf16_f32 v18, v18, v18
	v_lshl_add_u64 v[40:41], s[40:41], 0, v[40:41]
	global_store_short v[40:41], v18, off
	v_sub_u32_e32 v18, v86, v82
	v_cvt_f32_u32_e32 v42, v18
	v_cmp_lt_i32_e32 vcc, -1, v18
	v_mul_f32_e32 v42, v81, v42
	v_exp_f32_e32 v42, v42
	s_nop 0
	v_mul_f32_e32 v42, v42, v19
	v_cndmask_b32_e32 v42, 0, v42, vcc
	v_cmp_gt_i32_e32 vcc, 0, v18
	v_sub_u32_e32 v18, 0, v18
	v_cvt_f32_u32_e32 v18, v18
	v_cvt_pk_bf16_f32 v45, v42, v42
	v_mul_f32_e32 v18, v80, v18
	v_exp_f32_e32 v18, v18
	s_nop 0
	v_mul_f32_e32 v18, v18, v19
	v_cndmask_b32_e32 v44, 0, v18, vcc
	v_and_b32_e32 v18, 31, v86
	v_lshl_add_u32 v18, v18, 3, v101

; __device__ __forceinline__ unsigned cvt_pk_bf16(float lo, float hi) { unsigned r; asm volatile("v_cvt_pk_bf16_f32 %0, %1, %2" : "=v"(r) : "v"(lo), "v"(hi)); return r; }
; __device__ __forceinline__ int crow(int r, int h) { return (r & 3) + 8 * (r >> 2) + 4 * h; }
; __device__ __forceinline__ void ret_p_unit(const bf16_t* __restrict__ Q, const bf16_t* __restrict__ K, bf16_t* Pt, int b, int h, int ci, float lgf, float lgb) {
;     ...
;         for (int r = 0; r < 16; ++r) {
;             const int i = 32 * ib + crow(r, h2), j = 64 * jh + 32 * jb + l31, df = i - j;
;             const float v = s[jb][r];
;             const float vf = df >= 0 ? v * __builtin_amdgcn_exp2f((float)df * lgf) : 0.f;
;             const float vb = df < 0 ? v * __builtin_amdgcn_exp2f((float)(-df) * lgb) : 0.f;
;             pf[i * 128 + j] = (bf16_t)(cvt_pk_bf16(vf, vf) & 0xffffu);
;             pb[i * 128 + j] = (bf16_t)(cvt_pk_bf16(vb, vb) & 0xffffu);
	v_ashrrev_i32_e32 v19, 31, v18
	v_lshlrev_b64 v[42:43], 1, v[18:19]
	v_lshl_add_u64 v[18:19], s[16:17], 0, v[42:43]
	global_store_short v[18:19], v45, off
	v_cvt_pk_bf16_f32 v44, v44, v44
	v_lshl_add_u64 v[42:43], s[40:41], 0, v[42:43]
	global_store_short v[42:43], v44, off
	v_sub_u32_e32 v44, v87, v82
	v_cvt_f32_u32_e32 v45, v44
	v_cmp_lt_i32_e32 vcc, -1, v44
	v_mul_f32_e32 v45, v81, v45
	v_exp_f32_e32 v45, v45
	s_nop 0
	v_mul_f32_e32 v45, v45, v20
	v_cndmask_b32_e32 v45, 0, v45, vcc
	v_cmp_gt_i32_e32 vcc, 0, v44
	v_sub_u32_e32 v44, 0, v44
	v_cvt_f32_u32_e32 v44, v44
	v_cvt_pk_bf16_f32 v48, v45, v45
	v_mul_f32_e32 v44, v80, v44
	v_exp_f32_e32 v44, v44
	s_nop 0
	v_mul_f32_e32 v20, v44, v20
	v_and_b32_e32 v44, 31, v87
	v_lshl_add_u32 v44, v44, 3, v101

; __device__ __forceinline__ unsigned cvt_pk_bf16(float lo, float hi) { unsigned r; asm volatile("v_cvt_pk_bf16_f32 %0, %1, %2" : "=v"(r) : "v"(lo), "v"(hi)); return r; }
; __device__ __forceinline__ int crow(int r, int h) { return (r & 3) + 8 * (r >> 2) + 4 * h; }
; __device__ __forceinline__ void ret_p_unit(const bf16_t* __restrict__ Q, const bf16_t* __restrict__ K, bf16_t* Pt, int b, int h, int ci, float lgf, float lgb) {
;     ...
;         for (int r = 0; r < 16; ++r) {
;             const int i = 32 * ib + crow(r, h2), j = 64 * jh + 32 * jb + l31, df = i - j;
;             const float v = s[jb][r];
;             const float vf = df >= 0 ? v * __builtin_amdgcn_exp2f((float)df * lgf) : 0.f;
;             const float vb = df < 0 ? v * __builtin_amdgcn_exp2f((float)(-df) * lgb) : 0.f;
;             pf[i * 128 + j] = (bf16_t)(cvt_pk_bf16(vf, vf) & 0xffffu);
;             pb[i * 128 + j] = (bf16_t)(cvt_pk_bf16(vb, vb) & 0xffffu);
	v_ashrrev_i32_e32 v45, 31, v44
	v_lshlrev_b64 v[46:47], 1, v[44:45]
	v_cndmask_b32_e32 v20, 0, v20, vcc
	v_lshl_add_u64 v[44:45], s[16:17], 0, v[46:47]
	global_store_short v[44:45], v48, off
	v_cvt_pk_bf16_f32 v20, v20, v20
	v_lshl_add_u64 v[46:47], s[40:41], 0, v[46:47]
	global_store_short v[46:47], v20, off
	v_sub_u32_e32 v20, v88, v82
	v_cvt_f32_u32_e32 v48, v20
	v_cmp_lt_i32_e32 vcc, -1, v20
	v_mul_f32_e32 v48, v81, v48
	v_exp_f32_e32 v48, v48
	s_nop 0
	v_mul_f32_e32 v48, v48, v21
	v_cndmask_b32_e32 v48, 0, v48, vcc
	v_cmp_gt_i32_e32 vcc, 0, v20
	v_sub_u32_e32 v20, 0, v20
	v_cvt_f32_u32_e32 v20, v20
	v_cvt_pk_bf16_f32 v51, v48, v48
	v_mul_f32_e32 v20, v80, v20
	v_exp_f32_e32 v20, v20
	s_nop 0
	v_mul_f32_e32 v20, v20, v21
	v_cndmask_b32_e32 v50, 0, v20, vcc
	v_and_b32_e32 v20, 31, v88
	v_lshl_add_u32 v20, v20, 3, v101

; __device__ __forceinline__ unsigned cvt_pk_bf16(float lo, float hi) { unsigned r; asm volatile("v_cvt_pk_bf16_f32 %0, %1, %2" : "=v"(r) : "v"(lo), "v"(hi)); return r; }
; __device__ __forceinline__ int crow(int r, int h) { return (r & 3) + 8 * (r >> 2) + 4 * h; }
; __device__ __forceinline__ void ret_p_unit(const bf16_t* __restrict__ Q, const bf16_t* __restrict__ K, bf16_t* Pt, int b, int h, int ci, float lgf, float lgb) {
;     ...
;         for (int r = 0; r < 16; ++r) {
;             const int i = 32 * ib + crow(r, h2), j = 64 * jh + 32 * jb + l31, df = i - j;
;             const float v = s[jb][r];
;             const float vf = df >= 0 ? v * __builtin_amdgcn_exp2f((float)df * lgf) : 0.f;
;             const float vb = df < 0 ? v * __builtin_amdgcn_exp2f((float)(-df) * lgb) : 0.f;
;             pf[i * 128 + j] = (bf16_t)(cvt_pk_bf16(vf, vf) & 0xffffu);
;             pb[i * 128 + j] = (bf16_t)(cvt_pk_bf16(vb, vb) & 0xffffu);
	v_ashrrev_i32_e32 v21, 31, v20
	v_lshlrev_b64 v[48:49], 1, v[20:21]
	v_lshl_add_u64 v[20:21], s[16:17], 0, v[48:49]
	global_store_short v[20:21], v51, off
	v_cvt_pk_bf16_f32 v50, v50, v50
	v_lshl_add_u64 v[48:49], s[40:41], 0, v[48:49]
	global_store_short v[48:49], v50, off
	v_sub_u32_e32 v50, v89, v82
	v_cvt_f32_u32_e32 v51, v50
	v_cmp_lt_i32_e32 vcc, -1, v50
	v_mul_f32_e32 v51, v81, v51
	v_exp_f32_e32 v51, v51
	s_nop 0
	v_mul_f32_e32 v51, v51, v22
	v_cndmask_b32_e32 v51, 0, v51, vcc
	v_cmp_gt_i32_e32 vcc, 0, v50
	v_sub_u32_e32 v50, 0, v50
	v_cvt_f32_u32_e32 v50, v50
	v_cvt_pk_bf16_f32 v54, v51, v51
	v_mul_f32_e32 v50, v80, v50
	v_exp_f32_e32 v50, v50
	s_nop 0
	v_mul_f32_e32 v22, v50, v22
	v_and_b32_e32 v50, 31, v89
	v_lshl_add_u32 v50, v50, 3, v101

; __device__ __forceinline__ unsigned cvt_pk_bf16(float lo, float hi) { unsigned r; asm volatile("v_cvt_pk_bf16_f32 %0, %1, %2" : "=v"(r) : "v"(lo), "v"(hi)); return r; }
; __device__ __forceinline__ int crow(int r, int h) { return (r & 3) + 8 * (r >> 2) + 4 * h; }
; __device__ __forceinline__ void ret_p_unit(const bf16_t* __restrict__ Q, const bf16_t* __restrict__ K, bf16_t* Pt, int b, int h, int ci, float lgf, float lgb) {
;     ...
;         for (int r = 0; r < 16; ++r) {
;             const int i = 32 * ib + crow(r, h2), j = 64 * jh + 32 * jb + l31, df = i - j;
;             const float v = s[jb][r];
;             const float vf = df >= 0 ? v * __builtin_amdgcn_exp2f((float)df * lgf) : 0.f;
;             const float vb = df < 0 ? v * __builtin_amdgcn_exp2f((float)(-df) * lgb) : 0.f;
;             pf[i * 128 + j] = (bf16_t)(cvt_pk_bf16(vf, vf) & 0xffffu);
;             pb[i * 128 + j] = (bf16_t)(cvt_pk_bf16(vb, vb) & 0xffffu);
	v_ashrrev_i32_e32 v51, 31, v50
	v_lshlrev_b64 v[52:53], 1, v[50:51]
	v_cndmask_b32_e32 v22, 0, v22, vcc
	v_lshl_add_u64 v[50:51], s[16:17], 0, v[52:53]
	global_store_short v[50:51], v54, off
	v_cvt_pk_bf16_f32 v22, v22, v22
	v_lshl_add_u64 v[52:53], s[40:41], 0, v[52:53]
	global_store_short v[52:53], v22, off
	v_sub_u32_e32 v22, v90, v82
	v_cvt_f32_u32_e32 v54, v22
	v_cmp_lt_i32_e32 vcc, -1, v22
	v_mul_f32_e32 v54, v81, v54
	v_exp_f32_e32 v54, v54
	s_nop 0
	v_mul_f32_e32 v54, v54, v23
	v_cndmask_b32_e32 v54, 0, v54, vcc
	v_cmp_gt_i32_e32 vcc, 0, v22
	v_sub_u32_e32 v22, 0, v22
	v_cvt_f32_u32_e32 v22, v22
	v_cvt_pk_bf16_f32 v57, v54, v54
	v_mul_f32_e32 v22, v80, v22
	v_exp_f32_e32 v22, v22
	s_nop 0
	v_mul_f32_e32 v22, v22, v23
	v_cndmask_b32_e32 v56, 0, v22, vcc
	v_and_b32_e32 v22, 31, v90
	v_lshl_add_u32 v22, v22, 3, v101

; __device__ __forceinline__ unsigned cvt_pk_bf16(float lo, float hi) { unsigned r; asm volatile("v_cvt_pk_bf16_f32 %0, %1, %2" : "=v"(r) : "v"(lo), "v"(hi)); return r; }
; __device__ __forceinline__ int crow(int r, int h) { return (r & 3) + 8 * (r >> 2) + 4 * h; }
; __device__ __forceinline__ void ret_p_unit(const bf16_t* __restrict__ Q, const bf16_t* __restrict__ K, bf16_t* Pt, int b, int h, int ci, float lgf, float lgb) {
;     ...
;         for (int r = 0; r < 16; ++r) {
;             const int i = 32 * ib + crow(r, h2), j = 64 * jh + 32 * jb + l31, df = i - j;
;             const float v = s[jb][r];
;             const float vf = df >= 0 ? v * __builtin_amdgcn_exp2f((float)df * lgf) : 0.f;
;             const float vb = df < 0 ? v * __builtin_amdgcn_exp2f((float)(-df) * lgb) : 0.f;
;             pf[i * 128 + j] = (bf16_t)(cvt_pk_bf16(vf, vf) & 0xffffu);
;             pb[i * 128 + j] = (bf16_t)(cvt_pk_bf16(vb, vb) & 0xffffu);
	v_ashrrev_i32_e32 v23, 31, v22
	v_lshlrev_b64 v[54:55], 1, v[22:23]
	v_lshl_add_u64 v[22:23], s[16:17], 0, v[54:55]
	global_store_short v[22:23], v57, off
	v_cvt_pk_bf16_f32 v56, v56, v56
	v_lshl_add_u64 v[54:55], s[40:41], 0, v[54:55]
	global_store_short v[54:55], v56, off
	v_sub_u32_e32 v56, v91, v82
	v_cvt_f32_u32_e32 v57, v56
	v_cmp_lt_i32_e32 vcc, -1, v56
	v_mul_f32_e32 v57, v81, v57
	v_exp_f32_e32 v57, v57
	s_nop 0
	v_mul_f32_e32 v57, v57, v24
	v_cndmask_b32_e32 v57, 0, v57, vcc
	v_cmp_gt_i32_e32 vcc, 0, v56
	v_sub_u32_e32 v56, 0, v56
	v_cvt_f32_u32_e32 v56, v56
	v_cvt_pk_bf16_f32 v60, v57, v57
	v_mul_f32_e32 v56, v80, v56
	v_exp_f32_e32 v56, v56
	s_nop 0
	v_mul_f32_e32 v24, v56, v24
	v_and_b32_e32 v56, 31, v91
	v_lshl_add_u32 v56, v56, 3, v101

; __device__ __forceinline__ unsigned cvt_pk_bf16(float lo, float hi) { unsigned r; asm volatile("v_cvt_pk_bf16_f32 %0, %1, %2" : "=v"(r) : "v"(lo), "v"(hi)); return r; }
; __device__ __forceinline__ int crow(int r, int h) { return (r & 3) + 8 * (r >> 2) + 4 * h; }
; __device__ __forceinline__ void ret_p_unit(const bf16_t* __restrict__ Q, const bf16_t* __restrict__ K, bf16_t* Pt, int b, int h, int ci, float lgf, float lgb) {
;     ...
;         for (int r = 0; r < 16; ++r) {
;             const int i = 32 * ib + crow(r, h2), j = 64 * jh + 32 * jb + l31, df = i - j;
;             const float v = s[jb][r];
;             const float vf = df >= 0 ? v * __builtin_amdgcn_exp2f((float)df * lgf) : 0.f;
;             const float vb = df < 0 ? v * __builtin_amdgcn_exp2f((float)(-df) * lgb) : 0.f;
;             pf[i * 128 + j] = (bf16_t)(cvt_pk_bf16(vf, vf) & 0xffffu);
;             pb[i * 128 + j] = (bf16_t)(cvt_pk_bf16(vb, vb) & 0xffffu);
	v_ashrrev_i32_e32 v57, 31, v56
	v_lshlrev_b64 v[58:59], 1, v[56:57]
	v_cndmask_b32_e32 v24, 0, v24, vcc
	v_lshl_add_u64 v[56:57], s[16:17], 0, v[58:59]
	global_store_short v[56:57], v60, off
	v_cvt_pk_bf16_f32 v24, v24, v24
	v_lshl_add_u64 v[58:59], s[40:41], 0, v[58:59]
	global_store_short v[58:59], v24, off
	v_sub_u32_e32 v24, v92, v82
	v_cvt_f32_u32_e32 v60, v24
	v_cmp_lt_i32_e32 vcc, -1, v24
	v_mul_f32_e32 v60, v81, v60
	v_exp_f32_e32 v60, v60
	s_nop 0
	v_mul_f32_e32 v60, v60, v25
	v_cndmask_b32_e32 v60, 0, v60, vcc
	v_cmp_gt_i32_e32 vcc, 0, v24
	v_sub_u32_e32 v24, 0, v24
	v_cvt_f32_u32_e32 v24, v24
	v_cvt_pk_bf16_f32 v63, v60, v60
	v_mul_f32_e32 v24, v80, v24
	v_exp_f32_e32 v24, v24
	s_nop 0
	v_mul_f32_e32 v24, v24, v25
	v_cndmask_b32_e32 v62, 0, v24, vcc
	v_and_b32_e32 v24, 31, v92
	v_lshl_add_u32 v24, v24, 3, v101

; __device__ __forceinline__ unsigned cvt_pk_bf16(float lo, float hi) { unsigned r; asm volatile("v_cvt_pk_bf16_f32 %0, %1, %2" : "=v"(r) : "v"(lo), "v"(hi)); return r; }
; __device__ __forceinline__ int crow(int r, int h) { return (r & 3) + 8 * (r >> 2) + 4 * h; }
; __device__ __forceinline__ void ret_p_unit(const bf16_t* __restrict__ Q, const bf16_t* __restrict__ K, bf16_t* Pt, int b, int h, int ci, float lgf, float lgb) {
;     ...
;         for (int r = 0; r < 16; ++r) {
;             const int i = 32 * ib + crow(r, h2), j = 64 * jh + 32 * jb + l31, df = i - j;
;             const float v = s[jb][r];
;             const float vf = df >= 0 ? v * __builtin_amdgcn_exp2f((float)df * lgf) : 0.f;
;             const float vb = df < 0 ? v * __builtin_amdgcn_exp2f((float)(-df) * lgb) : 0.f;
;             pf[i * 128 + j] = (bf16_t)(cvt_pk_bf16(vf, vf) & 0xffffu);
;             pb[i * 128 + j] = (bf16_t)(cvt_pk_bf16(vb, vb) & 0xffffu);
	v_ashrrev_i32_e32 v25, 31, v24
	v_lshlrev_b64 v[60:61], 1, v[24:25]
	v_lshl_add_u64 v[24:25], s[16:17], 0, v[60:61]
	global_store_short v[24:25], v63, off
	v_cvt_pk_bf16_f32 v62, v62, v62
	v_lshl_add_u64 v[60:61], s[40:41], 0, v[60:61]
	global_store_short v[60:61], v62, off
	v_sub_u32_e32 v62, v93, v82
	v_cvt_f32_u32_e32 v63, v62
	v_cmp_lt_i32_e32 vcc, -1, v62
	v_mul_f32_e32 v63, v81, v63
	v_exp_f32_e32 v63, v63
	s_nop 0
	v_mul_f32_e32 v63, v63, v26
	v_cndmask_b32_e32 v63, 0, v63, vcc
	v_cmp_gt_i32_e32 vcc, 0, v62
	v_sub_u32_e32 v62, 0, v62
	v_cvt_f32_u32_e32 v62, v62
	v_cvt_pk_bf16_f32 v66, v63, v63
	v_mul_f32_e32 v62, v80, v62
	v_exp_f32_e32 v62, v62
	s_nop 0
	v_mul_f32_e32 v26, v62, v26
	v_and_b32_e32 v62, 31, v93
	v_lshl_add_u32 v62, v62, 3, v101

; __device__ __forceinline__ unsigned cvt_pk_bf16(float lo, float hi) { unsigned r; asm volatile("v_cvt_pk_bf16_f32 %0, %1, %2" : "=v"(r) : "v"(lo), "v"(hi)); return r; }
; __device__ __forceinline__ int crow(int r, int h) { return (r & 3) + 8 * (r >> 2) + 4 * h; }
; __device__ __forceinline__ void ret_p_unit(const bf16_t* __restrict__ Q, const bf16_t* __restrict__ K, bf16_t* Pt, int b, int h, int ci, float lgf, float lgb) {
;     ...
;         for (int r = 0; r < 16; ++r) {
;             const int i = 32 * ib + crow(r, h2), j = 64 * jh + 32 * jb + l31, df = i - j;
;             const float v = s[jb][r];
;             const float vf = df >= 0 ? v * __builtin_amdgcn_exp2f((float)df * lgf) : 0.f;
;             const float vb = df < 0 ? v * __builtin_amdgcn_exp2f((float)(-df) * lgb) : 0.f;
;             pf[i * 128 + j] = (bf16_t)(cvt_pk_bf16(vf, vf) & 0xffffu);
;             pb[i * 128 + j] = (bf16_t)(cvt_pk_bf16(vb, vb) & 0xffffu);
	v_ashrrev_i32_e32 v63, 31, v62
	v_lshlrev_b64 v[64:65], 1, v[62:63]
	v_cndmask_b32_e32 v26, 0, v26, vcc
	v_lshl_add_u64 v[62:63], s[16:17], 0, v[64:65]
	global_store_short v[62:63], v66, off
	v_cvt_pk_bf16_f32 v26, v26, v26
	v_lshl_add_u64 v[64:65], s[40:41], 0, v[64:65]
	global_store_short v[64:65], v26, off
	v_sub_u32_e32 v26, v94, v82
	v_cvt_f32_u32_e32 v66, v26
	v_cmp_lt_i32_e32 vcc, -1, v26
	v_mul_f32_e32 v66, v81, v66
	v_exp_f32_e32 v66, v66
	s_nop 0
	v_mul_f32_e32 v66, v66, v27
	v_cndmask_b32_e32 v66, 0, v66, vcc
	v_cmp_gt_i32_e32 vcc, 0, v26
	v_sub_u32_e32 v26, 0, v26
	v_cvt_f32_u32_e32 v26, v26
	v_cvt_pk_bf16_f32 v69, v66, v66
	v_mul_f32_e32 v26, v80, v26
	v_exp_f32_e32 v26, v26
	s_nop 0
	v_mul_f32_e32 v26, v26, v27
	v_cndmask_b32_e32 v68, 0, v26, vcc
	v_and_b32_e32 v26, 31, v94
	v_lshl_add_u32 v26, v26, 3, v101

; __device__ __forceinline__ unsigned cvt_pk_bf16(float lo, float hi) { unsigned r; asm volatile("v_cvt_pk_bf16_f32 %0, %1, %2" : "=v"(r) : "v"(lo), "v"(hi)); return r; }
; __device__ __forceinline__ int crow(int r, int h) { return (r & 3) + 8 * (r >> 2) + 4 * h; }
; __device__ __forceinline__ void ret_p_unit(const bf16_t* __restrict__ Q, const bf16_t* __restrict__ K, bf16_t* Pt, int b, int h, int ci, float lgf, float lgb) {
;     ...
;         for (int r = 0; r < 16; ++r) {
;             const int i = 32 * ib + crow(r, h2), j = 64 * jh + 32 * jb + l31, df = i - j;
;             const float v = s[jb][r];
;             const float vf = df >= 0 ? v * __builtin_amdgcn_exp2f((float)df * lgf) : 0.f;
;             const float vb = df < 0 ? v * __builtin_amdgcn_exp2f((float)(-df) * lgb) : 0.f;
;             pf[i * 128 + j] = (bf16_t)(cvt_pk_bf16(vf, vf) & 0xffffu);
;             pb[i * 128 + j] = (bf16_t)(cvt_pk_bf16(vb, vb) & 0xffffu);
	v_ashrrev_i32_e32 v27, 31, v26
	v_lshlrev_b64 v[66:67], 1, v[26:27]
	v_lshl_add_u64 v[26:27], s[16:17], 0, v[66:67]
	global_store_short v[26:27], v69, off
	v_cvt_pk_bf16_f32 v68, v68, v68
	v_lshl_add_u64 v[66:67], s[40:41], 0, v[66:67]
	global_store_short v[66:67], v68, off
	v_sub_u32_e32 v68, v95, v82
	v_cvt_f32_u32_e32 v69, v68
	v_cmp_lt_i32_e32 vcc, -1, v68
	v_mul_f32_e32 v69, v81, v69
	v_exp_f32_e32 v69, v69
	s_nop 0
	v_mul_f32_e32 v69, v69, v28
	v_cndmask_b32_e32 v69, 0, v69, vcc
	v_cmp_gt_i32_e32 vcc, 0, v68
	v_sub_u32_e32 v68, 0, v68
	v_cvt_f32_u32_e32 v68, v68
	v_cvt_pk_bf16_f32 v72, v69, v69
	v_mul_f32_e32 v68, v80, v68
	v_exp_f32_e32 v68, v68
	s_nop 0
	v_mul_f32_e32 v28, v68, v28
	v_and_b32_e32 v68, 31, v95
	v_lshl_add_u32 v68, v68, 3, v101

; __device__ __forceinline__ unsigned cvt_pk_bf16(float lo, float hi) { unsigned r; asm volatile("v_cvt_pk_bf16_f32 %0, %1, %2" : "=v"(r) : "v"(lo), "v"(hi)); return r; }
; __device__ __forceinline__ int crow(int r, int h) { return (r & 3) + 8 * (r >> 2) + 4 * h; }
; __device__ __forceinline__ void ret_p_unit(const bf16_t* __restrict__ Q, const bf16_t* __restrict__ K, bf16_t* Pt, int b, int h, int ci, float lgf, float lgb) {
;     ...
;         for (int r = 0; r < 16; ++r) {
;             const int i = 32 * ib + crow(r, h2), j = 64 * jh + 32 * jb + l31, df = i - j;
;             const float v = s[jb][r];
;             const float vf = df >= 0 ? v * __builtin_amdgcn_exp2f((float)df * lgf) : 0.f;
;             const float vb = df < 0 ? v * __builtin_amdgcn_exp2f((float)(-df) * lgb) : 0.f;
;             pf[i * 128 + j] = (bf16_t)(cvt_pk_bf16(vf, vf) & 0xffffu);
;             pb[i * 128 + j] = (bf16_t)(cvt_pk_bf16(vb, vb) & 0xffffu);
	v_ashrrev_i32_e32 v69, 31, v68
	v_lshlrev_b64 v[70:71], 1, v[68:69]
	v_cndmask_b32_e32 v28, 0, v28, vcc
	v_lshl_add_u64 v[68:69], s[16:17], 0, v[70:71]
	global_store_short v[68:69], v72, off
	v_cvt_pk_bf16_f32 v28, v28, v28
	v_lshl_add_u64 v[70:71], s[40:41], 0, v[70:71]
	global_store_short v[70:71], v28, off
	v_sub_u32_e32 v28, v96, v82
	v_cvt_f32_u32_e32 v72, v28
	v_cmp_lt_i32_e32 vcc, -1, v28
	v_mul_f32_e32 v72, v81, v72
	v_exp_f32_e32 v72, v72
	s_nop 0
	v_mul_f32_e32 v72, v72, v29
	v_cndmask_b32_e32 v72, 0, v72, vcc
	v_cmp_gt_i32_e32 vcc, 0, v28
	v_sub_u32_e32 v28, 0, v28
	v_cvt_f32_u32_e32 v28, v28
	v_cvt_pk_bf16_f32 v75, v72, v72
	v_mul_f32_e32 v28, v80, v28
	v_exp_f32_e32 v28, v28
	s_nop 0
	v_mul_f32_e32 v28, v28, v29
	v_cndmask_b32_e32 v74, 0, v28, vcc
	v_and_b32_e32 v28, 31, v96
	v_lshl_add_u32 v28, v28, 3, v101

; __device__ __forceinline__ unsigned cvt_pk_bf16(float lo, float hi) { unsigned r; asm volatile("v_cvt_pk_bf16_f32 %0, %1, %2" : "=v"(r) : "v"(lo), "v"(hi)); return r; }
; __device__ __forceinline__ int crow(int r, int h) { return (r & 3) + 8 * (r >> 2) + 4 * h; }
; __device__ __forceinline__ void ret_p_unit(const bf16_t* __restrict__ Q, const bf16_t* __restrict__ K, bf16_t* Pt, int b, int h, int ci, float lgf, float lgb) {
;     ...
;         for (int r = 0; r < 16; ++r) {
;             const int i = 32 * ib + crow(r, h2), j = 64 * jh + 32 * jb + l31, df = i - j;
;             const float v = s[jb][r];
;             const float vf = df >= 0 ? v * __builtin_amdgcn_exp2f((float)df * lgf) : 0.f;
;             const float vb = df < 0 ? v * __builtin_amdgcn_exp2f((float)(-df) * lgb) : 0.f;
;             pf[i * 128 + j] = (bf16_t)(cvt_pk_bf16(vf, vf) & 0xffffu);
;             pb[i * 128 + j] = (bf16_t)(cvt_pk_bf16(vb, vb) & 0xffffu);
	v_ashrrev_i32_e32 v29, 31, v28
	v_lshlrev_b64 v[72:73], 1, v[28:29]
	v_lshl_add_u64 v[28:29], s[16:17], 0, v[72:73]
	global_store_short v[28:29], v75, off
	v_cvt_pk_bf16_f32 v74, v74, v74
	v_lshl_add_u64 v[72:73], s[40:41], 0, v[72:73]
	global_store_short v[72:73], v74, off
	v_sub_u32_e32 v74, v97, v82
	v_cvt_f32_u32_e32 v75, v74
	v_cmp_lt_i32_e32 vcc, -1, v74
	v_mul_f32_e32 v75, v81, v75
	v_exp_f32_e32 v75, v75
	s_nop 0
	v_mul_f32_e32 v75, v75, v30
	v_cndmask_b32_e32 v75, 0, v75, vcc
	v_cmp_gt_i32_e32 vcc, 0, v74
	v_sub_u32_e32 v74, 0, v74
	v_cvt_f32_u32_e32 v74, v74
	v_cvt_pk_bf16_f32 v78, v75, v75
	v_mul_f32_e32 v74, v80, v74
	v_exp_f32_e32 v74, v74
	s_nop 0
	v_mul_f32_e32 v30, v74, v30
	v_and_b32_e32 v74, 31, v97
	v_lshl_add_u32 v74, v74, 3, v101

; __device__ __forceinline__ unsigned cvt_pk_bf16(float lo, float hi) { unsigned r; asm volatile("v_cvt_pk_bf16_f32 %0, %1, %2" : "=v"(r) : "v"(lo), "v"(hi)); return r; }
; __device__ __forceinline__ int crow(int r, int h) { return (r & 3) + 8 * (r >> 2) + 4 * h; }
; __device__ __forceinline__ void ret_p_unit(const bf16_t* __restrict__ Q, const bf16_t* __restrict__ K, bf16_t* Pt, int b, int h, int ci, float lgf, float lgb) {
;     ...
; #pragma unroll
;     for (int jb = 0; jb < 2; ++jb)
; #pragma unroll
;         for (int r = 0; r < 16; ++r) {
;             const int i = 32 * ib + crow(r, h2), j = 64 * jh + 32 * jb + l31, df = i - j;
;             const float v = s[jb][r];
;             const float vf = df >= 0 ? v * __builtin_amdgcn_exp2f((float)df * lgf) : 0.f;
;             const float vb = df < 0 ? v * __builtin_amdgcn_exp2f((float)(-df) * lgb) : 0.f;
;             pf[i * 128 + j] = (bf16_t)(cvt_pk_bf16(vf, vf) & 0xffffu);
;             pb[i * 128 + j] = (bf16_t)(cvt_pk_bf16(vb, vb) & 0xffffu);
	v_ashrrev_i32_e32 v75, 31, v74
	v_lshlrev_b64 v[76:77], 1, v[74:75]
	v_cndmask_b32_e32 v30, 0, v30, vcc
	v_lshl_add_u64 v[74:75], s[16:17], 0, v[76:77]
	global_store_short v[74:75], v78, off
	v_cvt_pk_bf16_f32 v30, v30, v30
	v_lshl_add_u64 v[76:77], s[40:41], 0, v[76:77]
	global_store_short v[76:77], v30, off
	v_sub_u32_e32 v30, v98, v82
	v_cvt_f32_u32_e32 v78, v30
	v_cmp_lt_i32_e32 vcc, -1, v30
	v_mul_f32_e32 v78, v81, v78
	v_exp_f32_e32 v78, v78
	s_nop 0
	v_mul_f32_e32 v78, v78, v31
	v_cndmask_b32_e32 v78, 0, v78, vcc
	v_cmp_gt_i32_e32 vcc, 0, v30
	v_sub_u32_e32 v30, 0, v30
	v_cvt_f32_u32_e32 v30, v30
	v_cvt_pk_bf16_f32 v100, v78, v78
	v_mul_f32_e32 v30, v80, v30
	v_exp_f32_e32 v30, v30
	s_nop 0
	v_mul_f32_e32 v30, v30, v31
	v_cndmask_b32_e32 v99, 0, v30, vcc
	v_and_b32_e32 v30, 31, v98
	v_lshl_add_u32 v30, v30, 3, v101

; __device__ __forceinline__ unsigned cvt_pk_bf16(float lo, float hi) { unsigned r; asm volatile("v_cvt_pk_bf16_f32 %0, %1, %2" : "=v"(r) : "v"(lo), "v"(hi)); return r; }
; __device__ __forceinline__ int crow(int r, int h) { return (r & 3) + 8 * (r >> 2) + 4 * h; }
; __device__ __forceinline__ void ret_p_unit(const bf16_t* __restrict__ Q, const bf16_t* __restrict__ K, bf16_t* Pt, int b, int h, int ci, float lgf, float lgb) {
;     ...
; #pragma unroll
;     for (int jb = 0; jb < 2; ++jb)
; #pragma unroll
;         for (int r = 0; r < 16; ++r) {
;             const int i = 32 * ib + crow(r, h2), j = 64 * jh + 32 * jb + l31, df = i - j;
;             const float v = s[jb][r];
;             const float vf = df >= 0 ? v * __builtin_amdgcn_exp2f((float)df * lgf) : 0.f;
;             const float vb = df < 0 ? v * __builtin_amdgcn_exp2f((float)(-df) * lgb) : 0.f;
;             pf[i * 128 + j] = (bf16_t)(cvt_pk_bf16(vf, vf) & 0xffffu);
;             pb[i * 128 + j] = (bf16_t)(cvt_pk_bf16(vb, vb) & 0xffffu);
;         }
	v_ashrrev_i32_e32 v31, 31, v30
	v_lshlrev_b64 v[78:79], 1, v[30:31]
	v_lshl_add_u64 v[30:31], s[16:17], 0, v[78:79]
	v_or_b32_e32 v82, 32, v82
	global_store_short v[30:31], v100, off
	v_cvt_pk_bf16_f32 v99, v99, v99
	v_lshl_add_u64 v[78:79], s[40:41], 0, v[78:79]
	v_sub_u32_e32 v83, v83, v82
	global_store_short v[78:79], v99, off
	v_cvt_f32_u32_e32 v99, v83
	v_cmp_lt_i32_e32 vcc, -1, v83
	v_mul_f32_e32 v99, v81, v99
	v_exp_f32_e32 v99, v99
	s_nop 0
	v_mul_f32_e32 v99, v99, v0
	v_cndmask_b32_e32 v99, 0, v99, vcc
	v_cmp_gt_i32_e32 vcc, 0, v83
	v_sub_u32_e32 v83, 0, v83
	v_cvt_f32_u32_e32 v83, v83
	v_mul_f32_e32 v83, v80, v83
	v_exp_f32_e32 v83, v83
	s_nop 0
	v_mul_f32_e32 v0, v83, v0
	v_cndmask_b32_e32 v0, 0, v0, vcc
	v_cvt_pk_bf16_f32 v83, v99, v99
	global_store_short v[32:33], v83, off offset:2048
	v_cvt_pk_bf16_f32 v0, v0, v0
	global_store_short v[34:35], v0, off offset:2048
	v_sub_u32_e32 v0, v84, v82
	v_cvt_f32_u32_e32 v32, v0
	v_cmp_lt_i32_e32 vcc, -1, v0
	v_mul_f32_e32 v32, v81, v32
	v_exp_f32_e32 v32, v32
	s_nop 0
	v_mul_f32_e32 v32, v32, v1
	v_cndmask_b32_e32 v32, 0, v32, vcc
	v_cmp_gt_i32_e32 vcc, 0, v0
	v_sub_u32_e32 v0, 0, v0
	v_cvt_f32_u32_e32 v0, v0
	v_mul_f32_e32 v0, v80, v0
	v_exp_f32_e32 v0, v0
	s_nop 0
	v_mul_f32_e32 v0, v0, v1
	v_cndmask_b32_e32 v0, 0, v0, vcc
	v_cvt_pk_bf16_f32 v1, v32, v32
	global_store_short v[16:17], v1, off offset:2048
	v_cvt_pk_bf16_f32 v0, v0, v0
	global_store_short v[36:37], v0, off offset:2048
	v_sub_u32_e32 v0, v85, v82
	v_cvt_f32_u32_e32 v1, v0
	v_cmp_lt_i32_e32 vcc, -1, v0
	v_mul_f32_e32 v1, v81, v1
	v_exp_f32_e32 v1, v1
	s_nop 0
	v_mul_f32_e32 v1, v1, v2
	v_cndmask_b32_e32 v1, 0, v1, vcc
	v_cmp_gt_i32_e32 vcc, 0, v0
	v_sub_u32_e32 v0, 0, v0
	v_cvt_f32_u32_e32 v0, v0
	v_cvt_pk_bf16_f32 v1, v1, v1
	global_store_short v[38:39], v1, off offset:2048
	v_mul_f32_e32 v0, v80, v0
	v_exp_f32_e32 v0, v0
	s_nop 0
	v_mul_f32_e32 v0, v0, v2
	v_cndmask_b32_e32 v0, 0, v0, vcc
	v_cvt_pk_bf16_f32 v0, v0, v0
	global_store_short v[40:41], v0, off offset:2048
	v_sub_u32_e32 v0, v86, v82
	v_cvt_f32_u32_e32 v1, v0
	v_cmp_lt_i32_e32 vcc, -1, v0
	v_mul_f32_e32 v1, v81, v1
	v_exp_f32_e32 v1, v1
	s_nop 0
	v_mul_f32_e32 v1, v1, v3
	v_cndmask_b32_e32 v1, 0, v1, vcc
	v_cmp_gt_i32_e32 vcc, 0, v0
	v_sub_u32_e32 v0, 0, v0
	v_cvt_f32_u32_e32 v0, v0
	v_cvt_pk_bf16_f32 v1, v1, v1
	global_store_short v[18:19], v1, off offset:2048
	v_mul_f32_e32 v0, v80, v0
	v_exp_f32_e32 v0, v0
	s_nop 0
	v_mul_f32_e32 v0, v0, v3
	v_cndmask_b32_e32 v0, 0, v0, vcc
	v_cvt_pk_bf16_f32 v0, v0, v0
	global_store_short v[42:43], v0, off offset:2048
	v_sub_u32_e32 v0, v87, v82
	v_cvt_f32_u32_e32 v1, v0
	v_cmp_lt_i32_e32 vcc, -1, v0
	v_mul_f32_e32 v1, v81, v1
	v_exp_f32_e32 v1, v1
	s_nop 0
	v_mul_f32_e32 v1, v1, v4
	v_cndmask_b32_e32 v1, 0, v1, vcc
	v_cmp_gt_i32_e32 vcc, 0, v0
	v_sub_u32_e32 v0, 0, v0
	v_cvt_f32_u32_e32 v0, v0
	v_cvt_pk_bf16_f32 v1, v1, v1
	global_store_short v[44:45], v1, off offset:2048
	v_mul_f32_e32 v0, v80, v0
	v_exp_f32_e32 v0, v0
	s_nop 0
	v_mul_f32_e32 v0, v0, v4
	v_cndmask_b32_e32 v0, 0, v0, vcc
	v_cvt_pk_bf16_f32 v0, v0, v0
	global_store_short v[46:47], v0, off offset:2048
	v_sub_u32_e32 v0, v88, v82
	v_cvt_f32_u32_e32 v1, v0
	v_cmp_lt_i32_e32 vcc, -1, v0
	v_mul_f32_e32 v1, v81, v1
	v_exp_f32_e32 v1, v1
	s_nop 0
	v_mul_f32_e32 v1, v1, v5
	v_cndmask_b32_e32 v1, 0, v1, vcc
	v_cmp_gt_i32_e32 vcc, 0, v0
	v_sub_u32_e32 v0, 0, v0
	v_cvt_f32_u32_e32 v0, v0
	v_cvt_pk_bf16_f32 v1, v1, v1
	global_store_short v[20:21], v1, off offset:2048
	v_mul_f32_e32 v0, v80, v0
	v_exp_f32_e32 v0, v0
	s_nop 0
	v_mul_f32_e32 v0, v0, v5
	v_cndmask_b32_e32 v0, 0, v0, vcc
	v_cvt_pk_bf16_f32 v0, v0, v0
	global_store_short v[48:49], v0, off offset:2048
	v_sub_u32_e32 v0, v89, v82
	v_cvt_f32_u32_e32 v1, v0
	v_cmp_lt_i32_e32 vcc, -1, v0
	v_mul_f32_e32 v1, v81, v1
	v_exp_f32_e32 v1, v1
	s_nop 0
	v_mul_f32_e32 v1, v1, v6
	v_cndmask_b32_e32 v1, 0, v1, vcc
	v_cmp_gt_i32_e32 vcc, 0, v0
	v_sub_u32_e32 v0, 0, v0
	v_cvt_f32_u32_e32 v0, v0
	v_cvt_pk_bf16_f32 v1, v1, v1
	global_store_short v[50:51], v1, off offset:2048
	v_mul_f32_e32 v0, v80, v0
	v_exp_f32_e32 v0, v0
	s_nop 0
	v_mul_f32_e32 v0, v0, v6
	v_cndmask_b32_e32 v0, 0, v0, vcc
	v_cvt_pk_bf16_f32 v0, v0, v0
	global_store_short v[52:53], v0, off offset:2048
	v_sub_u32_e32 v0, v90, v82
	v_cvt_f32_u32_e32 v1, v0
	v_cmp_lt_i32_e32 vcc, -1, v0
	v_mul_f32_e32 v1, v81, v1
	v_exp_f32_e32 v1, v1
	s_nop 0
	v_mul_f32_e32 v1, v1, v7
	v_cndmask_b32_e32 v1, 0, v1, vcc
	v_cmp_gt_i32_e32 vcc, 0, v0
	v_sub_u32_e32 v0, 0, v0
	v_cvt_f32_u32_e32 v0, v0
	v_cvt_pk_bf16_f32 v1, v1, v1
	global_store_short v[22:23], v1, off offset:2048
	v_mul_f32_e32 v0, v80, v0
	v_exp_f32_e32 v0, v0
; __device__ __forceinline__ unsigned cvt_pk_bf16(float lo, float hi) { unsigned r; asm volatile("v_cvt_pk_bf16_f32 %0, %1, %2" : "=v"(r) : "v"(lo), "v"(hi)); return r; }
; __device__ __forceinline__ int crow(int r, int h) { return (r & 3) + 8 * (r >> 2) + 4 * h; }
; __device__ __forceinline__ void ret_p_unit(const bf16_t* __restrict__ Q, const bf16_t* __restrict__ K, bf16_t* Pt, int b, int h, int ci, float lgf, float lgb) {
;     ...
; #pragma unroll
;     for (int jb = 0; jb < 2; ++jb)
; #pragma unroll
;         for (int r = 0; r < 16; ++r) {
;             const int i = 32 * ib + crow(r, h2), j = 64 * jh + 32 * jb + l31, df = i - j;
;             const float v = s[jb][r];
;             const float vf = df >= 0 ? v * __builtin_amdgcn_exp2f((float)df * lgf) : 0.f;
;             const float vb = df < 0 ? v * __builtin_amdgcn_exp2f((float)(-df) * lgb) : 0.f;
;             pf[i * 128 + j] = (bf16_t)(cvt_pk_bf16(vf, vf) & 0xffffu);
;             pb[i * 128 + j] = (bf16_t)(cvt_pk_bf16(vb, vb) & 0xffffu);
;         }
	s_nop 0
	v_mul_f32_e32 v0, v0, v7
	v_cndmask_b32_e32 v0, 0, v0, vcc
	v_cvt_pk_bf16_f32 v0, v0, v0
	global_store_short v[54:55], v0, off offset:2048
	v_sub_u32_e32 v0, v91, v82
	v_cvt_f32_u32_e32 v1, v0
	v_cmp_lt_i32_e32 vcc, -1, v0
	v_mul_f32_e32 v1, v81, v1
	v_exp_f32_e32 v1, v1
	s_nop 0
	v_mul_f32_e32 v1, v1, v8
	v_cndmask_b32_e32 v1, 0, v1, vcc
	v_cmp_gt_i32_e32 vcc, 0, v0
	v_sub_u32_e32 v0, 0, v0
	v_cvt_f32_u32_e32 v0, v0
	v_cvt_pk_bf16_f32 v1, v1, v1
	global_store_short v[56:57], v1, off offset:2048
	v_mul_f32_e32 v0, v80, v0
	v_exp_f32_e32 v0, v0
	s_nop 0
	v_mul_f32_e32 v0, v0, v8
	v_cndmask_b32_e32 v0, 0, v0, vcc
	v_cvt_pk_bf16_f32 v0, v0, v0
	global_store_short v[58:59], v0, off offset:2048
	v_sub_u32_e32 v0, v92, v82
	v_cvt_f32_u32_e32 v1, v0
	v_cmp_lt_i32_e32 vcc, -1, v0
	v_mul_f32_e32 v1, v81, v1
	v_exp_f32_e32 v1, v1
	s_nop 0
	v_mul_f32_e32 v1, v1, v9
	v_cndmask_b32_e32 v1, 0, v1, vcc
	v_cmp_gt_i32_e32 vcc, 0, v0
	v_sub_u32_e32 v0, 0, v0
	v_cvt_f32_u32_e32 v0, v0
	v_cvt_pk_bf16_f32 v1, v1, v1
	global_store_short v[24:25], v1, off offset:2048
	v_mul_f32_e32 v0, v80, v0
	v_exp_f32_e32 v0, v0
	s_nop 0
	v_mul_f32_e32 v0, v0, v9
	v_cndmask_b32_e32 v0, 0, v0, vcc
	v_cvt_pk_bf16_f32 v0, v0, v0
	global_store_short v[60:61], v0, off offset:2048
	v_sub_u32_e32 v0, v93, v82
	v_cvt_f32_u32_e32 v1, v0
	v_cmp_lt_i32_e32 vcc, -1, v0
	v_mul_f32_e32 v1, v81, v1
	v_exp_f32_e32 v1, v1
	s_nop 0
	v_mul_f32_e32 v1, v1, v10
	v_cndmask_b32_e32 v1, 0, v1, vcc
	v_cmp_gt_i32_e32 vcc, 0, v0
	v_sub_u32_e32 v0, 0, v0
	v_cvt_f32_u32_e32 v0, v0
	v_cvt_pk_bf16_f32 v1, v1, v1
	global_store_short v[62:63], v1, off offset:2048
	v_mul_f32_e32 v0, v80, v0
	v_exp_f32_e32 v0, v0
	s_nop 0
	v_mul_f32_e32 v0, v0, v10
	v_cndmask_b32_e32 v0, 0, v0, vcc
	v_cvt_pk_bf16_f32 v0, v0, v0
	global_store_short v[64:65], v0, off offset:2048
	v_sub_u32_e32 v0, v94, v82
	v_cvt_f32_u32_e32 v1, v0
	v_cmp_lt_i32_e32 vcc, -1, v0
	v_mul_f32_e32 v1, v81, v1
	v_exp_f32_e32 v1, v1
	s_nop 0
	v_mul_f32_e32 v1, v1, v11
	v_cndmask_b32_e32 v1, 0, v1, vcc
	v_cmp_gt_i32_e32 vcc, 0, v0
	v_sub_u32_e32 v0, 0, v0
	v_cvt_f32_u32_e32 v0, v0
	v_cvt_pk_bf16_f32 v1, v1, v1
	global_store_short v[26:27], v1, off offset:2048
	v_mul_f32_e32 v0, v80, v0
	v_exp_f32_e32 v0, v0
	s_nop 0
	v_mul_f32_e32 v0, v0, v11
	v_cndmask_b32_e32 v0, 0, v0, vcc
	v_cvt_pk_bf16_f32 v0, v0, v0
	global_store_short v[66:67], v0, off offset:2048
	v_sub_u32_e32 v0, v95, v82
	v_cvt_f32_u32_e32 v1, v0
	v_cmp_lt_i32_e32 vcc, -1, v0
	v_mul_f32_e32 v1, v81, v1
	v_exp_f32_e32 v1, v1
	s_nop 0
	v_mul_f32_e32 v1, v1, v12
	v_cndmask_b32_e32 v1, 0, v1, vcc
	v_cmp_gt_i32_e32 vcc, 0, v0
	v_sub_u32_e32 v0, 0, v0
	v_cvt_f32_u32_e32 v0, v0
	v_cvt_pk_bf16_f32 v1, v1, v1
	global_store_short v[68:69], v1, off offset:2048
	v_mul_f32_e32 v0, v80, v0
	v_exp_f32_e32 v0, v0
	s_nop 0
	v_mul_f32_e32 v0, v0, v12
	v_cndmask_b32_e32 v0, 0, v0, vcc
	v_cvt_pk_bf16_f32 v0, v0, v0
	global_store_short v[70:71], v0, off offset:2048
	v_sub_u32_e32 v0, v96, v82
	v_cvt_f32_u32_e32 v1, v0
	v_cmp_lt_i32_e32 vcc, -1, v0
	v_mul_f32_e32 v1, v81, v1
	v_exp_f32_e32 v1, v1
	s_nop 0
	v_mul_f32_e32 v1, v1, v13
	v_cndmask_b32_e32 v1, 0, v1, vcc
	v_cmp_gt_i32_e32 vcc, 0, v0
	v_sub_u32_e32 v0, 0, v0
	v_cvt_f32_u32_e32 v0, v0
	v_cvt_pk_bf16_f32 v1, v1, v1
	global_store_short v[28:29], v1, off offset:2048
	v_mul_f32_e32 v0, v80, v0
	v_exp_f32_e32 v0, v0
	s_nop 0
	v_mul_f32_e32 v0, v0, v13
	v_cndmask_b32_e32 v0, 0, v0, vcc
	v_cvt_pk_bf16_f32 v0, v0, v0
	global_store_short v[72:73], v0, off offset:2048
	v_sub_u32_e32 v0, v97, v82
	v_cvt_f32_u32_e32 v1, v0
	v_cmp_lt_i32_e32 vcc, -1, v0
	v_mul_f32_e32 v1, v81, v1
	v_exp_f32_e32 v1, v1
	s_nop 0
	v_mul_f32_e32 v1, v1, v14
	v_cndmask_b32_e32 v1, 0, v1, vcc
	v_cmp_gt_i32_e32 vcc, 0, v0
	v_sub_u32_e32 v0, 0, v0
	v_cvt_f32_u32_e32 v0, v0
	v_cvt_pk_bf16_f32 v1, v1, v1
	global_store_short v[74:75], v1, off offset:2048
	v_mul_f32_e32 v0, v80, v0
	v_exp_f32_e32 v0, v0
	s_nop 0
	v_mul_f32_e32 v0, v0, v14
	v_cndmask_b32_e32 v0, 0, v0, vcc
	v_cvt_pk_bf16_f32 v0, v0, v0
	global_store_short v[76:77], v0, off offset:2048
	v_sub_u32_e32 v0, v98, v82
	v_cvt_f32_u32_e32 v1, v0
	v_cmp_lt_i32_e32 vcc, -1, v0
	v_mul_f32_e32 v1, v81, v1
	v_exp_f32_e32 v1, v1
	s_nop 0
	v_mul_f32_e32 v1, v1, v15
	v_cndmask_b32_e32 v1, 0, v1, vcc
	v_cmp_gt_i32_e32 vcc, 0, v0
	v_sub_u32_e32 v0, 0, v0
	v_cvt_f32_u32_e32 v0, v0
	v_cvt_pk_bf16_f32 v1, v1, v1
	global_store_short v[30:31], v1, off offset:2048
	v_mul_f32_e32 v0, v80, v0
	v_exp_f32_e32 v0, v0
	s_nop 0
	v_mul_f32_e32 v0, v0, v15
	v_cndmask_b32_e32 v0, 0, v0, vcc
	v_cvt_pk_bf16_f32 v0, v0, v0
	global_store_short v[78:79], v0, off offset:2048
	s_cbranch_scc1 .LBB0_593
